# v10: v9 + the two per-iteration v_add_u32 (LDS read bases of buffer 1) hoisted out of all six GEMM K-loops into freed VGPRs
# baseline (speedup 1.0000x reference)
.LBB0_223:
	s_ashr_i32 s23, s22, 31
	s_lshl_b64 s[24:25], s[22:23], 20
	s_add_u32 s24, s81, s24
	s_addc_u32 s25, s85, s25
	s_and_b64 s[26:27], s[2:3], exec
	s_cselect_b32 s5, s25, s29
	s_cselect_b32 s7, s24, s28
	s_ashr_i32 s21, s20, 31
	s_lshl_b64 s[26:27], s[20:21], 20
	s_add_u32 s26, s92, s26
	s_addc_u32 s27, s97, s27
	s_and_b64 s[34:35], s[2:3], exec
	s_cselect_b32 s21, s27, s31
	s_cselect_b32 s23, s26, s30
	s_add_u32 s28, s28, 0x80080
	s_addc_u32 s29, s29, 0
	s_add_u32 s36, s30, 0x100
	v_mov_b32_e32 v2, 0
	s_addc_u32 s37, s31, 0
	s_mov_b32 s38, -2
	v_mov_b32_e32 v3, v2
	v_mov_b32_e32 v4, v2
	v_mov_b32_e32 v5, v2
	v_mov_b32_e32 v6, v2
	v_mov_b32_e32 v7, v2
	v_mov_b32_e32 v8, v2
	v_mov_b32_e32 v9, v2
	v_mov_b32_e32 v18, v2
	v_mov_b32_e32 v19, v2
	v_mov_b32_e32 v20, v2
	v_mov_b32_e32 v21, v2
	v_mov_b32_e32 v22, v2
	v_mov_b32_e32 v23, v2
	v_mov_b32_e32 v24, v2
	v_mov_b32_e32 v25, v2
	v_mov_b32_e32 v34, v2
	v_mov_b32_e32 v35, v2
	v_mov_b32_e32 v36, v2
	v_mov_b32_e32 v37, v2
	v_mov_b32_e32 v38, v2
	v_mov_b32_e32 v39, v2
	v_mov_b32_e32 v40, v2
	v_mov_b32_e32 v41, v2
	v_mov_b32_e32 v58, v2
	v_mov_b32_e32 v59, v2
	v_mov_b32_e32 v60, v2
	v_mov_b32_e32 v61, v2
	v_mov_b32_e32 v62, v2
	v_mov_b32_e32 v63, v2
	v_mov_b32_e32 v64, v2
	v_mov_b32_e32 v65, v2
	v_mov_b32_e32 v10, v2
	v_mov_b32_e32 v11, v2
	v_mov_b32_e32 v12, v2
	v_mov_b32_e32 v13, v2
	v_mov_b32_e32 v14, v2
	v_mov_b32_e32 v15, v2
	v_mov_b32_e32 v16, v2
	v_mov_b32_e32 v17, v2
	v_mov_b32_e32 v26, v2
	v_mov_b32_e32 v27, v2
	v_mov_b32_e32 v28, v2
	v_mov_b32_e32 v29, v2
	v_mov_b32_e32 v30, v2
	v_mov_b32_e32 v31, v2
	v_mov_b32_e32 v32, v2
	v_mov_b32_e32 v33, v2
	v_mov_b32_e32 v42, v2
	v_mov_b32_e32 v43, v2
	v_mov_b32_e32 v44, v2
	v_mov_b32_e32 v45, v2
	v_mov_b32_e32 v54, v2
	v_mov_b32_e32 v55, v2
	v_mov_b32_e32 v56, v2
	v_mov_b32_e32 v57, v2
	v_mov_b32_e32 v74, v2
	v_mov_b32_e32 v75, v2
	v_mov_b32_e32 v76, v2
	v_mov_b32_e32 v77, v2
	v_mov_b32_e32 v78, v2
	v_mov_b32_e32 v79, v2
	v_mov_b32_e32 v80, v2
	v_mov_b32_e32 v81, v2
	v_mov_b32_e32 v82, v2
	v_mov_b32_e32 v83, v2
	v_mov_b32_e32 v84, v2
	v_mov_b32_e32 v85, v2
	v_mov_b32_e32 v86, v2
	v_mov_b32_e32 v87, v2
	v_mov_b32_e32 v88, v2
	v_mov_b32_e32 v89, v2
	v_mov_b32_e32 v90, v2
	v_mov_b32_e32 v91, v2
	v_mov_b32_e32 v92, v2
	v_mov_b32_e32 v93, v2
	v_mov_b32_e32 v94, v2
	v_mov_b32_e32 v95, v2
	v_mov_b32_e32 v96, v2
	v_mov_b32_e32 v97, v2
	v_mov_b32_e32 v106, v2
	v_mov_b32_e32 v107, v2
	v_mov_b32_e32 v108, v2
	v_mov_b32_e32 v109, v2
	v_mov_b32_e32 v110, v2
	v_mov_b32_e32 v111, v2
	v_mov_b32_e32 v112, v2
	v_mov_b32_e32 v113, v2
	v_mov_b32_e32 v122, v2
	v_mov_b32_e32 v123, v2
	v_mov_b32_e32 v124, v2
	v_mov_b32_e32 v125, v2
	v_mov_b32_e32 v126, v2
	v_mov_b32_e32 v127, v2
	v_mov_b32_e32 v128, v2
	v_mov_b32_e32 v129, v2
	v_mov_b32_e32 v98, v2
	v_mov_b32_e32 v99, v2
	v_mov_b32_e32 v100, v2
	v_mov_b32_e32 v101, v2
	v_mov_b32_e32 v102, v2
	v_mov_b32_e32 v103, v2
	v_mov_b32_e32 v104, v2
	v_mov_b32_e32 v105, v2
	v_mov_b32_e32 v114, v2
	v_mov_b32_e32 v115, v2
	v_mov_b32_e32 v116, v2
	v_mov_b32_e32 v117, v2
	v_mov_b32_e32 v118, v2
	v_mov_b32_e32 v119, v2
	v_mov_b32_e32 v120, v2
	v_mov_b32_e32 v121, v2
	v_mov_b32_e32 v130, v2
	v_mov_b32_e32 v131, v2
	v_mov_b32_e32 v132, v2
	v_mov_b32_e32 v133, v2
	v_mov_b32_e32 v134, v2
	v_mov_b32_e32 v135, v2
	v_mov_b32_e32 v136, v2
	v_mov_b32_e32 v137, v2
	v_mov_b32_e32 v138, v2
	v_mov_b32_e32 v139, v2
	v_mov_b32_e32 v140, v2
	v_mov_b32_e32 v141, v2
	v_mov_b32_e32 v142, v2
	v_mov_b32_e32 v143, v2
	v_mov_b32_e32 v144, v2
	v_mov_b32_e32 v145, v2
	v_add_u32_e32 v180, 0x18000, v194
	v_add_u32_e32 v181, 0x1c000, v194
.LBB0_224:
	ds_read_b128 v[46:49], v196
	ds_read_b128 v[50:53], v196 offset:1024
	ds_read_b128 v[66:69], v196 offset:2048
	ds_read_b128 v[70:73], v196 offset:3072
	ds_read_b128 v[164:167], v197
	ds_read_b128 v[168:171], v197 offset:1024
	ds_read_b128 v[172:175], v197 offset:2048
	ds_read_b128 v[176:179], v197 offset:3072
	s_add_u32 s30, s28, 0xfff80080
	s_addc_u32 s31, s29, -1
	s_cmp_eq_u32 s38, 28
	s_cselect_b32 s35, s5, s31
	s_cselect_b32 s34, s7, s30
	s_cselect_b32 s31, s21, s37
	s_cselect_b32 s30, s23, s36
	s_add_i32 m0, s17, 0xc000
	ds_read_b128 v[184:187], v198
	ds_read_b128 v[188:191], v198 offset:1024
	ds_read_b128 v[200:203], v198 offset:2048
	ds_read_b128 v[204:207], v198 offset:3072
	ds_read_b128 v[208:211], v198 offset:4096
	ds_read_b128 v[212:215], v198 offset:5120
	ds_read_b128 v[216:219], v198 offset:6144
	ds_read_b128 v[220:223], v198 offset:7168
	global_load_lds_dwordx4 v156, s[28:29]
	s_add_i32 m0, s17, 0xe000
	s_nop 0
	global_load_lds_dwordx4 v158, s[28:29]
	s_waitcnt vmcnt(8)
	s_waitcnt lgkmcnt(0)
	s_barrier
	s_setprio 1
	s_waitcnt lgkmcnt(0)
	v_mfma_i32_16x16x64_i8 v[142:145], v[46:49], v[184:187], v[142:145]
	v_mfma_i32_16x16x64_i8 v[138:141], v[66:69], v[184:187], v[138:141]
	v_mfma_i32_16x16x64_i8 v[134:137], v[46:49], v[200:203], v[134:137]
	v_mfma_i32_16x16x64_i8 v[130:133], v[66:69], v[200:203], v[130:133]
	v_mfma_i32_16x16x64_i8 v[118:121], v[46:49], v[208:211], v[118:121]
	v_mfma_i32_16x16x64_i8 v[114:117], v[66:69], v[208:211], v[114:117]
	v_mfma_i32_16x16x64_i8 v[102:105], v[46:49], v[216:219], v[102:105]
	v_mfma_i32_16x16x64_i8 v[98:101], v[66:69], v[216:219], v[98:101]
	v_mfma_i32_16x16x64_i8 v[142:145], v[50:53], v[188:191], v[142:145]
	v_mfma_i32_16x16x64_i8 v[138:141], v[70:73], v[188:191], v[138:141]
	v_mfma_i32_16x16x64_i8 v[134:137], v[50:53], v[204:207], v[134:137]
	v_mfma_i32_16x16x64_i8 v[130:133], v[70:73], v[204:207], v[130:133]
	v_mfma_i32_16x16x64_i8 v[118:121], v[50:53], v[212:215], v[118:121]
	v_mfma_i32_16x16x64_i8 v[114:117], v[70:73], v[212:215], v[114:117]
	v_mfma_i32_16x16x64_i8 v[102:105], v[50:53], v[220:223], v[102:105]
	v_mfma_i32_16x16x64_i8 v[98:101], v[70:73], v[220:223], v[98:101]
	s_setprio 0
	s_setprio 1
	v_mfma_i32_16x16x64_i8 v[126:129], v[164:167], v[184:187], v[126:129]
	v_mfma_i32_16x16x64_i8 v[122:125], v[172:175], v[184:187], v[122:125]
	v_mfma_i32_16x16x64_i8 v[110:113], v[164:167], v[200:203], v[110:113]
	v_mfma_i32_16x16x64_i8 v[106:109], v[172:175], v[200:203], v[106:109]
	v_mfma_i32_16x16x64_i8 v[94:97], v[164:167], v[208:211], v[94:97]
	v_mfma_i32_16x16x64_i8 v[90:93], v[172:175], v[208:211], v[90:93]
	v_mfma_i32_16x16x64_i8 v[86:89], v[164:167], v[216:219], v[86:89]
	v_mfma_i32_16x16x64_i8 v[82:85], v[172:175], v[216:219], v[82:85]
	v_mfma_i32_16x16x64_i8 v[126:129], v[168:171], v[188:191], v[126:129]
	v_mfma_i32_16x16x64_i8 v[122:125], v[176:179], v[188:191], v[122:125]
	v_mfma_i32_16x16x64_i8 v[110:113], v[168:171], v[204:207], v[110:113]
	v_mfma_i32_16x16x64_i8 v[106:109], v[176:179], v[204:207], v[106:109]
	v_mfma_i32_16x16x64_i8 v[94:97], v[168:171], v[212:215], v[94:97]
	v_mfma_i32_16x16x64_i8 v[90:93], v[176:179], v[212:215], v[90:93]
	v_mfma_i32_16x16x64_i8 v[86:89], v[168:171], v[220:223], v[86:89]
	v_mfma_i32_16x16x64_i8 v[82:85], v[176:179], v[220:223], v[82:85]
	s_setprio 0
	s_barrier
	s_add_i32 s39, s76, s9
	s_mov_b32 m0, s39
	ds_read_b128 v[184:187], v198 offset:16384
	ds_read_b128 v[188:191], v198 offset:17408
	ds_read_b128 v[200:203], v198 offset:18432
	ds_read_b128 v[204:207], v198 offset:19456
	ds_read_b128 v[208:211], v198 offset:20480
	ds_read_b128 v[212:215], v198 offset:21504
	ds_read_b128 v[216:219], v198 offset:22528
	ds_read_b128 v[220:223], v198 offset:23552
	global_load_lds_dwordx4 v146, s[30:31]
	s_add_i32 m0, s39, 0x2000
	s_add_u32 s46, s30, 0x80000
	s_addc_u32 s47, s31, 0
	s_add_i32 s39, s77, s9
	global_load_lds_dwordx4 v148, s[30:31]
	s_mov_b32 m0, s39
	s_nop 0
	global_load_lds_dwordx4 v146, s[46:47]
	s_add_i32 m0, s39, 0x2000
	s_nop 0
	global_load_lds_dwordx4 v148, s[46:47]
	s_mov_b32 m0, s17
	s_nop 0
	global_load_lds_dwordx4 v146, s[34:35]
	s_mov_b32 m0, s40
	s_nop 0
	global_load_lds_dwordx4 v148, s[34:35]
	s_waitcnt vmcnt(8)
	s_waitcnt lgkmcnt(0)
	s_barrier
	s_setprio 1
	s_waitcnt lgkmcnt(0)
	v_mfma_i32_16x16x64_i8 v[78:81], v[46:49], v[184:187], v[78:81]
	v_mfma_i32_16x16x64_i8 v[74:77], v[66:69], v[184:187], v[74:77]
	v_mfma_i32_16x16x64_i8 v[54:57], v[46:49], v[200:203], v[54:57]
	v_mfma_i32_16x16x64_i8 v[42:45], v[66:69], v[200:203], v[42:45]
	v_mfma_i32_16x16x64_i8 v[30:33], v[46:49], v[208:211], v[30:33]
	v_mfma_i32_16x16x64_i8 v[26:29], v[66:69], v[208:211], v[26:29]
	v_mfma_i32_16x16x64_i8 v[14:17], v[46:49], v[216:219], v[14:17]
	v_mfma_i32_16x16x64_i8 v[10:13], v[66:69], v[216:219], v[10:13]
	v_mfma_i32_16x16x64_i8 v[78:81], v[50:53], v[188:191], v[78:81]
	v_mfma_i32_16x16x64_i8 v[74:77], v[70:73], v[188:191], v[74:77]
	v_mfma_i32_16x16x64_i8 v[54:57], v[50:53], v[204:207], v[54:57]
	v_mfma_i32_16x16x64_i8 v[42:45], v[70:73], v[204:207], v[42:45]
	v_mfma_i32_16x16x64_i8 v[30:33], v[50:53], v[212:215], v[30:33]
	v_mfma_i32_16x16x64_i8 v[26:29], v[70:73], v[212:215], v[26:29]
	v_mfma_i32_16x16x64_i8 v[14:17], v[50:53], v[220:223], v[14:17]
	v_mfma_i32_16x16x64_i8 v[10:13], v[70:73], v[220:223], v[10:13]
	s_setprio 0
	s_setprio 1
	v_mfma_i32_16x16x64_i8 v[38:41], v[164:167], v[200:203], v[38:41]
	v_mfma_i32_16x16x64_i8 v[34:37], v[172:175], v[200:203], v[34:37]
	v_mfma_i32_16x16x64_i8 v[22:25], v[164:167], v[208:211], v[22:25]
	v_mfma_i32_16x16x64_i8 v[18:21], v[172:175], v[208:211], v[18:21]
	v_mfma_i32_16x16x64_i8 v[6:9], v[164:167], v[216:219], v[6:9]
	v_mfma_i32_16x16x64_i8 v[2:5], v[172:175], v[216:219], v[2:5]
	v_mfma_i32_16x16x64_i8 v[46:49], v[164:167], v[184:187], v[62:65]
	v_mfma_i32_16x16x64_i8 v[50:53], v[172:175], v[184:187], v[58:61]
	v_mfma_i32_16x16x64_i8 v[38:41], v[168:171], v[204:207], v[38:41]
	v_mfma_i32_16x16x64_i8 v[34:37], v[176:179], v[204:207], v[34:37]
	v_mfma_i32_16x16x64_i8 v[22:25], v[168:171], v[212:215], v[22:25]
	v_mfma_i32_16x16x64_i8 v[18:21], v[176:179], v[212:215], v[18:21]
	v_mfma_i32_16x16x64_i8 v[6:9], v[168:171], v[220:223], v[6:9]
	v_mfma_i32_16x16x64_i8 v[2:5], v[176:179], v[220:223], v[2:5]
	v_mfma_i32_16x16x64_i8 v[46:49], v[168:171], v[188:191], v[46:49]
	v_mfma_i32_16x16x64_i8 v[50:53], v[176:179], v[188:191], v[50:53]
	s_setprio 0
	s_barrier
	s_add_i32 s39, 0, 0x18000
	s_add_i32 s46, 0, 0x1c000
	ds_read_b128 v[58:61], v180
	ds_read_b128 v[62:65], v180 offset:1024
	ds_read_b128 v[66:69], v180 offset:2048
	ds_read_b128 v[70:73], v180 offset:3072
	ds_read_b128 v[164:167], v181
	ds_read_b128 v[168:171], v181 offset:1024
	ds_read_b128 v[172:175], v181 offset:2048
	ds_read_b128 v[176:179], v181 offset:3072
	s_add_u32 s34, s34, 0x80000
	s_addc_u32 s35, s35, 0
	s_mov_b32 m0, s41
	ds_read_b128 v[184:187], v198 offset:32768
	ds_read_b128 v[188:191], v198 offset:33792
	ds_read_b128 v[200:203], v198 offset:34816
	ds_read_b128 v[204:207], v198 offset:35840
	ds_read_b128 v[208:211], v198 offset:36864
	ds_read_b128 v[212:215], v198 offset:37888
	ds_read_b128 v[216:219], v198 offset:38912
	ds_read_b128 v[220:223], v198 offset:39936
	global_load_lds_dwordx4 v146, s[34:35]
	s_mov_b32 m0, s42
	s_nop 0
	global_load_lds_dwordx4 v148, s[34:35]
	s_waitcnt vmcnt(8)
	s_waitcnt lgkmcnt(0)
	s_barrier
	s_setprio 1
	s_waitcnt lgkmcnt(0)
	v_mfma_i32_16x16x64_i8 v[142:145], v[58:61], v[184:187], v[142:145]
	v_mfma_i32_16x16x64_i8 v[138:141], v[66:69], v[184:187], v[138:141]
	v_mfma_i32_16x16x64_i8 v[134:137], v[58:61], v[200:203], v[134:137]
	v_mfma_i32_16x16x64_i8 v[130:133], v[66:69], v[200:203], v[130:133]
	v_mfma_i32_16x16x64_i8 v[118:121], v[58:61], v[208:211], v[118:121]
	v_mfma_i32_16x16x64_i8 v[114:117], v[66:69], v[208:211], v[114:117]
	v_mfma_i32_16x16x64_i8 v[102:105], v[58:61], v[216:219], v[102:105]
	v_mfma_i32_16x16x64_i8 v[98:101], v[66:69], v[216:219], v[98:101]
	v_mfma_i32_16x16x64_i8 v[142:145], v[62:65], v[188:191], v[142:145]
	v_mfma_i32_16x16x64_i8 v[138:141], v[70:73], v[188:191], v[138:141]
	v_mfma_i32_16x16x64_i8 v[134:137], v[62:65], v[204:207], v[134:137]
	v_mfma_i32_16x16x64_i8 v[130:133], v[70:73], v[204:207], v[130:133]
	v_mfma_i32_16x16x64_i8 v[118:121], v[62:65], v[212:215], v[118:121]
	v_mfma_i32_16x16x64_i8 v[114:117], v[70:73], v[212:215], v[114:117]
	v_mfma_i32_16x16x64_i8 v[102:105], v[62:65], v[220:223], v[102:105]
	v_mfma_i32_16x16x64_i8 v[98:101], v[70:73], v[220:223], v[98:101]
	s_setprio 0
	s_setprio 1
	v_mfma_i32_16x16x64_i8 v[126:129], v[164:167], v[184:187], v[126:129]
	v_mfma_i32_16x16x64_i8 v[122:125], v[172:175], v[184:187], v[122:125]
	v_mfma_i32_16x16x64_i8 v[110:113], v[164:167], v[200:203], v[110:113]
	v_mfma_i32_16x16x64_i8 v[106:109], v[172:175], v[200:203], v[106:109]
	v_mfma_i32_16x16x64_i8 v[94:97], v[164:167], v[208:211], v[94:97]
	v_mfma_i32_16x16x64_i8 v[90:93], v[172:175], v[208:211], v[90:93]
	v_mfma_i32_16x16x64_i8 v[86:89], v[164:167], v[216:219], v[86:89]
	v_mfma_i32_16x16x64_i8 v[82:85], v[172:175], v[216:219], v[82:85]
	v_mfma_i32_16x16x64_i8 v[126:129], v[168:171], v[188:191], v[126:129]
	v_mfma_i32_16x16x64_i8 v[122:125], v[176:179], v[188:191], v[122:125]
	v_mfma_i32_16x16x64_i8 v[110:113], v[168:171], v[204:207], v[110:113]
	v_mfma_i32_16x16x64_i8 v[106:109], v[176:179], v[204:207], v[106:109]
	v_mfma_i32_16x16x64_i8 v[94:97], v[168:171], v[212:215], v[94:97]
	v_mfma_i32_16x16x64_i8 v[90:93], v[176:179], v[212:215], v[90:93]
	v_mfma_i32_16x16x64_i8 v[86:89], v[168:171], v[220:223], v[86:89]
	v_mfma_i32_16x16x64_i8 v[82:85], v[176:179], v[220:223], v[82:85]
	s_setprio 0
	s_barrier
	s_add_u32 s98, s34, 0xfff80080
	s_addc_u32 s99, s35, -1
	s_add_i32 s34, s39, s9
	s_mov_b32 m0, s34
	ds_read_b128 v[184:187], v198 offset:49152
	ds_read_b128 v[188:191], v198 offset:50176
	ds_read_b128 v[200:203], v198 offset:51200
	ds_read_b128 v[204:207], v198 offset:52224
	ds_read_b128 v[208:211], v198 offset:53248
	ds_read_b128 v[212:215], v198 offset:54272
	ds_read_b128 v[216:219], v198 offset:55296
	ds_read_b128 v[220:223], v198 offset:56320
	s_add_u32 s100, s30, 0x80
	s_addc_u32 s101, s31, 0
	global_load_lds_dwordx4 v146, s[100:101]
	s_add_i32 m0, s34, 0x2000
	s_add_u32 s30, s30, 0x80080
	s_addc_u32 s31, s31, 0
	s_add_i32 s34, s46, s9
	global_load_lds_dwordx4 v148, s[100:101]
	s_mov_b32 m0, s34
	s_nop 0
	global_load_lds_dwordx4 v146, s[30:31]
	s_add_i32 m0, s34, 0x2000
	s_nop 0
	global_load_lds_dwordx4 v148, s[30:31]
	s_mov_b32 m0, s72
	s_nop 0
	global_load_lds_dwordx4 v146, s[98:99]
	s_mov_b32 m0, s73
	s_nop 0
	global_load_lds_dwordx4 v148, s[98:99]
	s_waitcnt vmcnt(8)
	s_waitcnt lgkmcnt(0)
	s_barrier
	s_setprio 1
	s_waitcnt lgkmcnt(0)
	v_mfma_i32_16x16x64_i8 v[78:81], v[58:61], v[184:187], v[78:81]
	v_mfma_i32_16x16x64_i8 v[74:77], v[66:69], v[184:187], v[74:77]
	v_mfma_i32_16x16x64_i8 v[54:57], v[58:61], v[200:203], v[54:57]
	v_mfma_i32_16x16x64_i8 v[42:45], v[66:69], v[200:203], v[42:45]
	v_mfma_i32_16x16x64_i8 v[30:33], v[58:61], v[208:211], v[30:33]
	v_mfma_i32_16x16x64_i8 v[26:29], v[66:69], v[208:211], v[26:29]
	v_mfma_i32_16x16x64_i8 v[14:17], v[58:61], v[216:219], v[14:17]
	v_mfma_i32_16x16x64_i8 v[10:13], v[66:69], v[216:219], v[10:13]
	v_mfma_i32_16x16x64_i8 v[78:81], v[62:65], v[188:191], v[78:81]
	v_mfma_i32_16x16x64_i8 v[74:77], v[70:73], v[188:191], v[74:77]
	v_mfma_i32_16x16x64_i8 v[54:57], v[62:65], v[204:207], v[54:57]
	v_mfma_i32_16x16x64_i8 v[42:45], v[70:73], v[204:207], v[42:45]
	v_mfma_i32_16x16x64_i8 v[30:33], v[62:65], v[212:215], v[30:33]
	v_mfma_i32_16x16x64_i8 v[26:29], v[70:73], v[212:215], v[26:29]
	v_mfma_i32_16x16x64_i8 v[14:17], v[62:65], v[220:223], v[14:17]
	v_mfma_i32_16x16x64_i8 v[10:13], v[70:73], v[220:223], v[10:13]
	s_setprio 0
	s_setprio 1
	v_mfma_i32_16x16x64_i8 v[46:49], v[164:167], v[184:187], v[46:49]
	v_mfma_i32_16x16x64_i8 v[62:65], v[168:171], v[188:191], v[46:49]
	v_mfma_i32_16x16x64_i8 v[46:49], v[172:175], v[184:187], v[50:53]
	v_mfma_i32_16x16x64_i8 v[38:41], v[164:167], v[200:203], v[38:41]
	v_mfma_i32_16x16x64_i8 v[34:37], v[172:175], v[200:203], v[34:37]
	v_mfma_i32_16x16x64_i8 v[22:25], v[164:167], v[208:211], v[22:25]
	v_mfma_i32_16x16x64_i8 v[18:21], v[172:175], v[208:211], v[18:21]
	v_mfma_i32_16x16x64_i8 v[6:9], v[164:167], v[216:219], v[6:9]
	v_mfma_i32_16x16x64_i8 v[2:5], v[172:175], v[216:219], v[2:5]
	v_mfma_i32_16x16x64_i8 v[58:61], v[176:179], v[188:191], v[46:49]
	v_mfma_i32_16x16x64_i8 v[38:41], v[168:171], v[204:207], v[38:41]
	v_mfma_i32_16x16x64_i8 v[34:37], v[176:179], v[204:207], v[34:37]
	v_mfma_i32_16x16x64_i8 v[22:25], v[168:171], v[212:215], v[22:25]
	v_mfma_i32_16x16x64_i8 v[18:21], v[176:179], v[212:215], v[18:21]
	v_mfma_i32_16x16x64_i8 v[6:9], v[168:171], v[220:223], v[6:9]
	v_mfma_i32_16x16x64_i8 v[2:5], v[176:179], v[220:223], v[2:5]
	s_setprio 0
	s_barrier
	s_add_i32 s38, s38, 2
	s_add_u32 s28, s28, 0x100
	s_addc_u32 s29, s29, 0
	s_add_u32 s36, s36, 0x100
	s_addc_u32 s37, s37, 0
	s_cmp_gt_u32 s38, 29
	s_cbranch_scc0 .LBB0_224
	s_and_b64 vcc, exec, s[14:15]
	s_cbranch_vccz .LBB0_227
	s_barrier

.LBB0_549:
	s_ashr_i32 s25, s24, 31
	s_lshl_b64 s[26:27], s[24:25], 19
	s_add_u32 s26, s48, s26
	s_addc_u32 s27, s49, s27
	s_and_b64 s[28:29], s[2:3], exec
	s_cselect_b32 s25, s27, s35
	s_cselect_b32 s70, s26, s34
	s_ashr_i32 s23, s22, 31
	s_lshl_b64 s[28:29], s[22:23], 19
	v_readlane_b32 s72, v254, 10
	s_add_u32 s28, s72, s28
	s_addc_u32 s29, s79, s29
	s_and_b64 s[38:39], s[2:3], exec
	s_cselect_b32 s23, s29, s37
	s_cselect_b32 s71, s28, s36
	s_add_u32 s34, s34, 0x40080
	s_addc_u32 s35, s35, 0
	v_readlane_b32 s73, v254, 11
	v_readlane_b32 s74, v254, 12
	s_add_u32 s72, s36, 0x100
	v_mov_b32_e32 v2, 0
	s_addc_u32 s73, s37, 0
	s_mov_b32 s74, -2
	v_mov_b32_e32 v3, v2
	v_mov_b32_e32 v4, v2
	v_mov_b32_e32 v5, v2
	v_mov_b32_e32 v6, v2
	v_mov_b32_e32 v7, v2
	v_mov_b32_e32 v8, v2
	v_mov_b32_e32 v9, v2
	v_mov_b32_e32 v18, v2
	v_mov_b32_e32 v19, v2
	v_mov_b32_e32 v20, v2
	v_mov_b32_e32 v21, v2
	v_mov_b32_e32 v22, v2
	v_mov_b32_e32 v23, v2
	v_mov_b32_e32 v24, v2
	v_mov_b32_e32 v25, v2
	v_mov_b32_e32 v34, v2
	v_mov_b32_e32 v35, v2
	v_mov_b32_e32 v36, v2
	v_mov_b32_e32 v37, v2
	v_mov_b32_e32 v38, v2
	v_mov_b32_e32 v39, v2
	v_mov_b32_e32 v40, v2
	v_mov_b32_e32 v41, v2
	s_waitcnt vmcnt(0)
	v_mov_b32_e32 v50, v2
	v_mov_b32_e32 v51, v2
	v_mov_b32_e32 v52, v2
	v_mov_b32_e32 v53, v2
	v_mov_b32_e32 v54, v2
	v_mov_b32_e32 v55, v2
	v_mov_b32_e32 v56, v2
	v_mov_b32_e32 v57, v2
	v_mov_b32_e32 v10, v2
	v_mov_b32_e32 v11, v2
	v_mov_b32_e32 v12, v2
	v_mov_b32_e32 v13, v2
	v_mov_b32_e32 v14, v2
	v_mov_b32_e32 v15, v2
	v_mov_b32_e32 v16, v2
	v_mov_b32_e32 v17, v2
	v_mov_b32_e32 v26, v2
	v_mov_b32_e32 v27, v2
	v_mov_b32_e32 v28, v2
	v_mov_b32_e32 v29, v2
	v_mov_b32_e32 v30, v2
	v_mov_b32_e32 v31, v2
	v_mov_b32_e32 v32, v2
	v_mov_b32_e32 v33, v2
	v_mov_b32_e32 v42, v2
	v_mov_b32_e32 v43, v2
	v_mov_b32_e32 v44, v2
	v_mov_b32_e32 v45, v2
	v_mov_b32_e32 v46, v2
	v_mov_b32_e32 v47, v2
	v_mov_b32_e32 v48, v2
	v_mov_b32_e32 v49, v2
	v_mov_b32_e32 v58, v2
	v_mov_b32_e32 v59, v2
	v_mov_b32_e32 v60, v2
	v_mov_b32_e32 v61, v2
	v_mov_b32_e32 v62, v2
	v_mov_b32_e32 v63, v2
	v_mov_b32_e32 v64, v2
	v_mov_b32_e32 v65, v2
	v_mov_b32_e32 v66, v2
	v_mov_b32_e32 v67, v2
	v_mov_b32_e32 v68, v2
	v_mov_b32_e32 v69, v2
	v_mov_b32_e32 v70, v2
	v_mov_b32_e32 v71, v2
	v_mov_b32_e32 v72, v2
	v_mov_b32_e32 v73, v2
	v_mov_b32_e32 v82, v2
	v_mov_b32_e32 v83, v2
	v_mov_b32_e32 v84, v2
	v_mov_b32_e32 v85, v2
	v_mov_b32_e32 v86, v2
	v_mov_b32_e32 v87, v2
	v_mov_b32_e32 v88, v2
	v_mov_b32_e32 v89, v2
	v_mov_b32_e32 v98, v2
	v_mov_b32_e32 v99, v2
	v_mov_b32_e32 v100, v2
	v_mov_b32_e32 v101, v2
	v_mov_b32_e32 v102, v2
	v_mov_b32_e32 v103, v2
	v_mov_b32_e32 v104, v2
	v_mov_b32_e32 v105, v2
	v_mov_b32_e32 v130, v2
	v_mov_b32_e32 v131, v2
	v_mov_b32_e32 v132, v2
	v_mov_b32_e32 v133, v2
	v_mov_b32_e32 v134, v2
	v_mov_b32_e32 v135, v2
	v_mov_b32_e32 v136, v2
	v_mov_b32_e32 v137, v2
	v_mov_b32_e32 v74, v2
	v_mov_b32_e32 v75, v2
	v_mov_b32_e32 v76, v2
	v_mov_b32_e32 v77, v2
	v_mov_b32_e32 v78, v2
	v_mov_b32_e32 v79, v2
	v_mov_b32_e32 v80, v2
	v_mov_b32_e32 v81, v2
	v_mov_b32_e32 v90, v2
	v_mov_b32_e32 v91, v2
	v_mov_b32_e32 v92, v2
	v_mov_b32_e32 v93, v2
	v_mov_b32_e32 v94, v2
	v_mov_b32_e32 v95, v2
	v_mov_b32_e32 v96, v2
	v_mov_b32_e32 v97, v2
	v_mov_b32_e32 v122, v2
	v_mov_b32_e32 v123, v2
	v_mov_b32_e32 v124, v2
	v_mov_b32_e32 v125, v2
	v_mov_b32_e32 v126, v2
	v_mov_b32_e32 v127, v2
	v_mov_b32_e32 v128, v2
	v_mov_b32_e32 v129, v2
	v_mov_b32_e32 v138, v2
	v_mov_b32_e32 v139, v2
	v_mov_b32_e32 v140, v2
	v_mov_b32_e32 v141, v2
	v_mov_b32_e32 v142, v2
	v_mov_b32_e32 v143, v2
	v_mov_b32_e32 v144, v2
	v_mov_b32_e32 v145, v2
	v_readlane_b32 s75, v254, 13
	v_add_u32_e32 v162, 0x18000, v195
	v_add_u32_e32 v163, 0x1c000, v195
.LBB0_550:
	ds_read_b128 v[106:109], v147
	ds_read_b128 v[110:113], v147 offset:1024
	ds_read_b128 v[114:117], v147 offset:2048
	ds_read_b128 v[118:121], v147 offset:3072
	ds_read_b128 v[174:177], v197
	ds_read_b128 v[200:203], v197 offset:1024
	ds_read_b128 v[204:207], v197 offset:2048
	ds_read_b128 v[208:211], v197 offset:3072
	s_add_u32 s36, s34, 0xfffc0080
	s_addc_u32 s37, s35, -1
	s_cmp_eq_u32 s74, 12
	s_cselect_b32 s39, s25, s37
	s_cselect_b32 s38, s70, s36
	s_cselect_b32 s37, s23, s73
	s_cselect_b32 s36, s71, s72
	s_add_i32 m0, s31, 0xc000
	ds_read_b128 v[212:215], v198
	ds_read_b128 v[216:219], v198 offset:1024
	ds_read_b128 v[220:223], v198 offset:2048
	ds_read_b128 v[224:227], v198 offset:3072
	ds_read_b128 v[228:231], v198 offset:4096
	ds_read_b128 v[232:235], v198 offset:5120
	ds_read_b128 v[236:239], v198 offset:6144
	ds_read_b128 v[240:243], v198 offset:7168
	global_load_lds_dwordx4 v154, s[34:35]
	s_add_i32 m0, s31, 0xe000
	s_nop 0
	global_load_lds_dwordx4 v156, s[34:35]
	s_waitcnt vmcnt(8)
	s_waitcnt lgkmcnt(0)
	s_barrier
	s_setprio 1
	s_waitcnt lgkmcnt(0)
	v_mfma_i32_16x16x64_i8 v[142:145], v[106:109], v[212:215], v[142:145]
	v_mfma_i32_16x16x64_i8 v[138:141], v[114:117], v[212:215], v[138:141]
	v_mfma_i32_16x16x64_i8 v[126:129], v[106:109], v[220:223], v[126:129]
	v_mfma_i32_16x16x64_i8 v[122:125], v[114:117], v[220:223], v[122:125]
	v_mfma_i32_16x16x64_i8 v[94:97], v[106:109], v[228:231], v[94:97]
	v_mfma_i32_16x16x64_i8 v[90:93], v[114:117], v[228:231], v[90:93]
	v_mfma_i32_16x16x64_i8 v[78:81], v[106:109], v[236:239], v[78:81]
	v_mfma_i32_16x16x64_i8 v[74:77], v[114:117], v[236:239], v[74:77]
	v_mfma_i32_16x16x64_i8 v[142:145], v[110:113], v[216:219], v[142:145]
	v_mfma_i32_16x16x64_i8 v[138:141], v[118:121], v[216:219], v[138:141]
	v_mfma_i32_16x16x64_i8 v[126:129], v[110:113], v[224:227], v[126:129]
	v_mfma_i32_16x16x64_i8 v[122:125], v[118:121], v[224:227], v[122:125]
	v_mfma_i32_16x16x64_i8 v[94:97], v[110:113], v[232:235], v[94:97]
	v_mfma_i32_16x16x64_i8 v[90:93], v[118:121], v[232:235], v[90:93]
	v_mfma_i32_16x16x64_i8 v[78:81], v[110:113], v[240:243], v[78:81]
	v_mfma_i32_16x16x64_i8 v[74:77], v[118:121], v[240:243], v[74:77]
	s_setprio 0
	s_setprio 1
	v_mfma_i32_16x16x64_i8 v[134:137], v[174:177], v[212:215], v[134:137]
	v_mfma_i32_16x16x64_i8 v[130:133], v[204:207], v[212:215], v[130:133]
	v_mfma_i32_16x16x64_i8 v[102:105], v[174:177], v[220:223], v[102:105]
	v_mfma_i32_16x16x64_i8 v[98:101], v[204:207], v[220:223], v[98:101]
	v_mfma_i32_16x16x64_i8 v[86:89], v[174:177], v[228:231], v[86:89]
	v_mfma_i32_16x16x64_i8 v[82:85], v[204:207], v[228:231], v[82:85]
	v_mfma_i32_16x16x64_i8 v[70:73], v[174:177], v[236:239], v[70:73]
	v_mfma_i32_16x16x64_i8 v[66:69], v[204:207], v[236:239], v[66:69]
	v_mfma_i32_16x16x64_i8 v[134:137], v[200:203], v[216:219], v[134:137]
	v_mfma_i32_16x16x64_i8 v[130:133], v[208:211], v[216:219], v[130:133]
	v_mfma_i32_16x16x64_i8 v[102:105], v[200:203], v[224:227], v[102:105]
	v_mfma_i32_16x16x64_i8 v[98:101], v[208:211], v[224:227], v[98:101]
	v_mfma_i32_16x16x64_i8 v[86:89], v[200:203], v[232:235], v[86:89]
	v_mfma_i32_16x16x64_i8 v[82:85], v[208:211], v[232:235], v[82:85]
	v_mfma_i32_16x16x64_i8 v[70:73], v[200:203], v[240:243], v[70:73]
	v_mfma_i32_16x16x64_i8 v[66:69], v[208:211], v[240:243], v[66:69]
	s_setprio 0
	s_barrier
	s_add_i32 s75, s67, s41
	s_mov_b32 m0, s75
	ds_read_b128 v[212:215], v198 offset:16384
	ds_read_b128 v[216:219], v198 offset:17408
	ds_read_b128 v[220:223], v198 offset:18432
	ds_read_b128 v[224:227], v198 offset:19456
	ds_read_b128 v[228:231], v198 offset:20480
	ds_read_b128 v[232:235], v198 offset:21504
	ds_read_b128 v[236:239], v198 offset:22528
	ds_read_b128 v[240:243], v198 offset:23552
	global_load_lds_dwordx4 v148, s[36:37]
	s_add_i32 m0, s75, 0x2000
	s_add_u32 s76, s36, 0x40000
	s_addc_u32 s77, s37, 0
	s_add_i32 s75, s68, s41
	global_load_lds_dwordx4 v150, s[36:37]
	s_mov_b32 m0, s75
	s_nop 0
	global_load_lds_dwordx4 v148, s[76:77]
	s_add_i32 m0, s75, 0x2000
	s_nop 0
	global_load_lds_dwordx4 v150, s[76:77]
	s_mov_b32 m0, s31
	s_nop 0
	global_load_lds_dwordx4 v148, s[38:39]
	s_mov_b32 m0, s42
	s_nop 0
	global_load_lds_dwordx4 v150, s[38:39]
	s_waitcnt vmcnt(8)
	s_waitcnt lgkmcnt(0)
	s_barrier
	s_setprio 1
	s_waitcnt lgkmcnt(0)
	v_mfma_i32_16x16x64_i8 v[62:65], v[106:109], v[212:215], v[62:65]
	v_mfma_i32_16x16x64_i8 v[58:61], v[114:117], v[212:215], v[58:61]
	v_mfma_i32_16x16x64_i8 v[46:49], v[106:109], v[220:223], v[46:49]
	v_mfma_i32_16x16x64_i8 v[42:45], v[114:117], v[220:223], v[42:45]
	v_mfma_i32_16x16x64_i8 v[30:33], v[106:109], v[228:231], v[30:33]
	v_mfma_i32_16x16x64_i8 v[26:29], v[114:117], v[228:231], v[26:29]
	v_mfma_i32_16x16x64_i8 v[14:17], v[106:109], v[236:239], v[14:17]
	v_mfma_i32_16x16x64_i8 v[10:13], v[114:117], v[236:239], v[10:13]
	v_mfma_i32_16x16x64_i8 v[62:65], v[110:113], v[216:219], v[62:65]
	v_mfma_i32_16x16x64_i8 v[58:61], v[118:121], v[216:219], v[58:61]
	v_mfma_i32_16x16x64_i8 v[46:49], v[110:113], v[224:227], v[46:49]
	v_mfma_i32_16x16x64_i8 v[42:45], v[118:121], v[224:227], v[42:45]
	v_mfma_i32_16x16x64_i8 v[30:33], v[110:113], v[232:235], v[30:33]
	v_mfma_i32_16x16x64_i8 v[26:29], v[118:121], v[232:235], v[26:29]
	v_mfma_i32_16x16x64_i8 v[14:17], v[110:113], v[240:243], v[14:17]
	v_mfma_i32_16x16x64_i8 v[10:13], v[118:121], v[240:243], v[10:13]
	s_setprio 0
	s_setprio 1
	v_mfma_i32_16x16x64_i8 v[54:57], v[174:177], v[212:215], v[54:57]
	v_mfma_i32_16x16x64_i8 v[50:53], v[204:207], v[212:215], v[50:53]
	v_mfma_i32_16x16x64_i8 v[38:41], v[174:177], v[220:223], v[38:41]
	v_mfma_i32_16x16x64_i8 v[34:37], v[204:207], v[220:223], v[34:37]
	v_mfma_i32_16x16x64_i8 v[22:25], v[174:177], v[228:231], v[22:25]
	v_mfma_i32_16x16x64_i8 v[18:21], v[204:207], v[228:231], v[18:21]
	v_mfma_i32_16x16x64_i8 v[6:9], v[174:177], v[236:239], v[6:9]
	v_mfma_i32_16x16x64_i8 v[2:5], v[204:207], v[236:239], v[2:5]
	v_mfma_i32_16x16x64_i8 v[54:57], v[200:203], v[216:219], v[54:57]
	v_mfma_i32_16x16x64_i8 v[50:53], v[208:211], v[216:219], v[50:53]
	v_mfma_i32_16x16x64_i8 v[38:41], v[200:203], v[224:227], v[38:41]
	v_mfma_i32_16x16x64_i8 v[34:37], v[208:211], v[224:227], v[34:37]
	v_mfma_i32_16x16x64_i8 v[22:25], v[200:203], v[232:235], v[22:25]
	v_mfma_i32_16x16x64_i8 v[18:21], v[208:211], v[232:235], v[18:21]
	v_mfma_i32_16x16x64_i8 v[6:9], v[200:203], v[240:243], v[6:9]
	v_mfma_i32_16x16x64_i8 v[2:5], v[208:211], v[240:243], v[2:5]
	s_setprio 0
	s_barrier
	s_add_i32 s75, 0, 0x18000
	s_add_i32 s76, 0, 0x1c000
	ds_read_b128 v[106:109], v162
	ds_read_b128 v[110:113], v162 offset:1024
	ds_read_b128 v[114:117], v162 offset:2048
	ds_read_b128 v[118:121], v162 offset:3072
	ds_read_b128 v[174:177], v163
	ds_read_b128 v[200:203], v163 offset:1024
	ds_read_b128 v[204:207], v163 offset:2048
	ds_read_b128 v[208:211], v163 offset:3072
	s_add_u32 s38, s38, 0x40000
	s_addc_u32 s39, s39, 0
	s_mov_b32 m0, s43
	ds_read_b128 v[212:215], v198 offset:32768
	ds_read_b128 v[216:219], v198 offset:33792
	ds_read_b128 v[220:223], v198 offset:34816
	ds_read_b128 v[224:227], v198 offset:35840
	ds_read_b128 v[228:231], v198 offset:36864
	ds_read_b128 v[232:235], v198 offset:37888
	ds_read_b128 v[236:239], v198 offset:38912
	ds_read_b128 v[240:243], v198 offset:39936
	global_load_lds_dwordx4 v148, s[38:39]
	s_mov_b32 m0, s46
	s_nop 0
	global_load_lds_dwordx4 v150, s[38:39]
	s_waitcnt vmcnt(8)
	s_waitcnt lgkmcnt(0)
	s_barrier
	s_setprio 1
	s_waitcnt lgkmcnt(0)
	v_mfma_i32_16x16x64_i8 v[142:145], v[106:109], v[212:215], v[142:145]
	v_mfma_i32_16x16x64_i8 v[138:141], v[114:117], v[212:215], v[138:141]
	v_mfma_i32_16x16x64_i8 v[126:129], v[106:109], v[220:223], v[126:129]
	v_mfma_i32_16x16x64_i8 v[122:125], v[114:117], v[220:223], v[122:125]
	v_mfma_i32_16x16x64_i8 v[94:97], v[106:109], v[228:231], v[94:97]
	v_mfma_i32_16x16x64_i8 v[90:93], v[114:117], v[228:231], v[90:93]
	v_mfma_i32_16x16x64_i8 v[78:81], v[106:109], v[236:239], v[78:81]
	v_mfma_i32_16x16x64_i8 v[74:77], v[114:117], v[236:239], v[74:77]
	v_mfma_i32_16x16x64_i8 v[142:145], v[110:113], v[216:219], v[142:145]
	v_mfma_i32_16x16x64_i8 v[138:141], v[118:121], v[216:219], v[138:141]
	v_mfma_i32_16x16x64_i8 v[126:129], v[110:113], v[224:227], v[126:129]
	v_mfma_i32_16x16x64_i8 v[122:125], v[118:121], v[224:227], v[122:125]
	v_mfma_i32_16x16x64_i8 v[94:97], v[110:113], v[232:235], v[94:97]
	v_mfma_i32_16x16x64_i8 v[90:93], v[118:121], v[232:235], v[90:93]
	v_mfma_i32_16x16x64_i8 v[78:81], v[110:113], v[240:243], v[78:81]
	v_mfma_i32_16x16x64_i8 v[74:77], v[118:121], v[240:243], v[74:77]
	s_setprio 0
	s_setprio 1
	v_mfma_i32_16x16x64_i8 v[134:137], v[174:177], v[212:215], v[134:137]
	v_mfma_i32_16x16x64_i8 v[130:133], v[204:207], v[212:215], v[130:133]
	v_mfma_i32_16x16x64_i8 v[102:105], v[174:177], v[220:223], v[102:105]
	v_mfma_i32_16x16x64_i8 v[98:101], v[204:207], v[220:223], v[98:101]
	v_mfma_i32_16x16x64_i8 v[86:89], v[174:177], v[228:231], v[86:89]
	v_mfma_i32_16x16x64_i8 v[82:85], v[204:207], v[228:231], v[82:85]
	v_mfma_i32_16x16x64_i8 v[70:73], v[174:177], v[236:239], v[70:73]
	v_mfma_i32_16x16x64_i8 v[66:69], v[204:207], v[236:239], v[66:69]
	v_mfma_i32_16x16x64_i8 v[134:137], v[200:203], v[216:219], v[134:137]
	v_mfma_i32_16x16x64_i8 v[130:133], v[208:211], v[216:219], v[130:133]
	v_mfma_i32_16x16x64_i8 v[102:105], v[200:203], v[224:227], v[102:105]
	v_mfma_i32_16x16x64_i8 v[98:101], v[208:211], v[224:227], v[98:101]
	v_mfma_i32_16x16x64_i8 v[86:89], v[200:203], v[232:235], v[86:89]
	v_mfma_i32_16x16x64_i8 v[82:85], v[208:211], v[232:235], v[82:85]
	v_mfma_i32_16x16x64_i8 v[70:73], v[200:203], v[240:243], v[70:73]
	v_mfma_i32_16x16x64_i8 v[66:69], v[208:211], v[240:243], v[66:69]
	s_setprio 0
	s_barrier
	s_add_u32 s98, s38, 0xfffc0080
	s_addc_u32 s99, s39, -1
	s_add_i32 s38, s75, s41
	s_mov_b32 m0, s38
	ds_read_b128 v[212:215], v198 offset:49152
	ds_read_b128 v[216:219], v198 offset:50176
	ds_read_b128 v[220:223], v198 offset:51200
	ds_read_b128 v[224:227], v198 offset:52224
	ds_read_b128 v[228:231], v198 offset:53248
	ds_read_b128 v[232:235], v198 offset:54272
	ds_read_b128 v[236:239], v198 offset:55296
	ds_read_b128 v[240:243], v198 offset:56320
	s_add_u32 s100, s36, 0x80
	s_addc_u32 s101, s37, 0
	global_load_lds_dwordx4 v148, s[100:101]
	s_add_i32 m0, s38, 0x2000
	s_add_u32 s36, s36, 0x40080
	s_addc_u32 s37, s37, 0
	s_add_i32 s38, s76, s41
	global_load_lds_dwordx4 v150, s[100:101]
	s_mov_b32 m0, s38
	s_nop 0
	global_load_lds_dwordx4 v148, s[36:37]
	s_add_i32 m0, s38, 0x2000
	s_nop 0
	global_load_lds_dwordx4 v150, s[36:37]
	s_mov_b32 m0, s56
	s_nop 0
	global_load_lds_dwordx4 v148, s[98:99]
	s_mov_b32 m0, s57
	s_nop 0
	global_load_lds_dwordx4 v150, s[98:99]
	s_waitcnt vmcnt(8)
	s_waitcnt lgkmcnt(0)
	s_barrier
	s_setprio 1
	s_waitcnt lgkmcnt(0)
	v_mfma_i32_16x16x64_i8 v[62:65], v[106:109], v[212:215], v[62:65]
	v_mfma_i32_16x16x64_i8 v[58:61], v[114:117], v[212:215], v[58:61]
	v_mfma_i32_16x16x64_i8 v[46:49], v[106:109], v[220:223], v[46:49]
	v_mfma_i32_16x16x64_i8 v[42:45], v[114:117], v[220:223], v[42:45]
	v_mfma_i32_16x16x64_i8 v[30:33], v[106:109], v[228:231], v[30:33]
	v_mfma_i32_16x16x64_i8 v[26:29], v[114:117], v[228:231], v[26:29]
	v_mfma_i32_16x16x64_i8 v[14:17], v[106:109], v[236:239], v[14:17]
	v_mfma_i32_16x16x64_i8 v[10:13], v[114:117], v[236:239], v[10:13]
	v_mfma_i32_16x16x64_i8 v[62:65], v[110:113], v[216:219], v[62:65]
	v_mfma_i32_16x16x64_i8 v[58:61], v[118:121], v[216:219], v[58:61]
	v_mfma_i32_16x16x64_i8 v[46:49], v[110:113], v[224:227], v[46:49]
	v_mfma_i32_16x16x64_i8 v[42:45], v[118:121], v[224:227], v[42:45]
	v_mfma_i32_16x16x64_i8 v[30:33], v[110:113], v[232:235], v[30:33]
	v_mfma_i32_16x16x64_i8 v[26:29], v[118:121], v[232:235], v[26:29]
	v_mfma_i32_16x16x64_i8 v[14:17], v[110:113], v[240:243], v[14:17]
	v_mfma_i32_16x16x64_i8 v[10:13], v[118:121], v[240:243], v[10:13]
	s_setprio 0
	s_setprio 1
	v_mfma_i32_16x16x64_i8 v[54:57], v[174:177], v[212:215], v[54:57]
	v_mfma_i32_16x16x64_i8 v[50:53], v[204:207], v[212:215], v[50:53]
	v_mfma_i32_16x16x64_i8 v[38:41], v[174:177], v[220:223], v[38:41]
	v_mfma_i32_16x16x64_i8 v[34:37], v[204:207], v[220:223], v[34:37]
	v_mfma_i32_16x16x64_i8 v[22:25], v[174:177], v[228:231], v[22:25]
	v_mfma_i32_16x16x64_i8 v[18:21], v[204:207], v[228:231], v[18:21]
	v_mfma_i32_16x16x64_i8 v[6:9], v[174:177], v[236:239], v[6:9]
	v_mfma_i32_16x16x64_i8 v[2:5], v[204:207], v[236:239], v[2:5]
	v_mfma_i32_16x16x64_i8 v[54:57], v[200:203], v[216:219], v[54:57]
	v_mfma_i32_16x16x64_i8 v[50:53], v[208:211], v[216:219], v[50:53]
	v_mfma_i32_16x16x64_i8 v[38:41], v[200:203], v[224:227], v[38:41]
	v_mfma_i32_16x16x64_i8 v[34:37], v[208:211], v[224:227], v[34:37]
	v_mfma_i32_16x16x64_i8 v[22:25], v[200:203], v[232:235], v[22:25]
	v_mfma_i32_16x16x64_i8 v[18:21], v[208:211], v[232:235], v[18:21]
	v_mfma_i32_16x16x64_i8 v[6:9], v[200:203], v[240:243], v[6:9]
	v_mfma_i32_16x16x64_i8 v[2:5], v[208:211], v[240:243], v[2:5]
	s_setprio 0
	s_barrier
	s_add_i32 s74, s74, 2
	s_add_u32 s34, s34, 0x100
	s_addc_u32 s35, s35, 0
	s_add_u32 s72, s72, 0x100
	s_addc_u32 s73, s73, 0
	s_cmp_gt_u32 s74, 13
	s_cbranch_scc0 .LBB0_550
	s_and_b64 vcc, exec, s[10:11]
	s_cbranch_vccz .LBB0_553
	s_barrier

.LBB0_573:
	s_ashr_i32 s13, s12, 31
	s_lshl_b64 s[14:15], s[12:13], 18
	s_add_u32 s14, s30, s14
	s_addc_u32 s15, s31, s15
	s_and_b64 s[16:17], s[2:3], exec
	s_cselect_b32 s13, s15, s23
	s_cselect_b32 s46, s14, s22
	s_ashr_i32 s11, s10, 31
	s_lshl_b64 s[16:17], s[10:11], 18
	v_readlane_b32 s68, v254, 4
	s_add_u32 s16, s68, s16
	s_addc_u32 s17, s78, s17
	s_and_b64 s[26:27], s[2:3], exec
	s_cselect_b32 s11, s17, s25
	s_cselect_b32 s47, s16, s24
	s_add_u32 s22, s22, 0x20080
	s_addc_u32 s23, s23, 0
	s_add_u32 s56, s24, 0x100
	v_mov_b32_e32 v2, 0
	s_addc_u32 s57, s25, 0
	s_mov_b32 s66, -2
	v_mov_b32_e32 v3, v2
	v_mov_b32_e32 v4, v2
	v_mov_b32_e32 v5, v2
	v_mov_b32_e32 v6, v2
	v_mov_b32_e32 v7, v2
	v_mov_b32_e32 v8, v2
	v_mov_b32_e32 v9, v2
	v_mov_b32_e32 v18, v2
	v_mov_b32_e32 v19, v2
	v_mov_b32_e32 v20, v2
	v_mov_b32_e32 v21, v2
	v_mov_b32_e32 v22, v2
	v_mov_b32_e32 v23, v2
	v_mov_b32_e32 v24, v2
	v_mov_b32_e32 v25, v2
	v_mov_b32_e32 v34, v2
	v_mov_b32_e32 v35, v2
	v_mov_b32_e32 v36, v2
	v_mov_b32_e32 v37, v2
	v_mov_b32_e32 v38, v2
	v_mov_b32_e32 v39, v2
	v_mov_b32_e32 v40, v2
	v_mov_b32_e32 v41, v2
	s_waitcnt vmcnt(0)
	v_mov_b32_e32 v50, v2
	v_mov_b32_e32 v51, v2
	v_mov_b32_e32 v52, v2
	v_mov_b32_e32 v53, v2
	v_mov_b32_e32 v54, v2
	v_mov_b32_e32 v55, v2
	v_mov_b32_e32 v56, v2
	v_mov_b32_e32 v57, v2
	v_mov_b32_e32 v10, v2
	v_mov_b32_e32 v11, v2
	v_mov_b32_e32 v12, v2
	v_mov_b32_e32 v13, v2
	v_mov_b32_e32 v14, v2
	v_mov_b32_e32 v15, v2
	v_mov_b32_e32 v16, v2
	v_mov_b32_e32 v17, v2
	v_mov_b32_e32 v26, v2
	v_mov_b32_e32 v27, v2
	v_mov_b32_e32 v28, v2
	v_mov_b32_e32 v29, v2
	v_mov_b32_e32 v30, v2
	v_mov_b32_e32 v31, v2
	v_mov_b32_e32 v32, v2
	v_mov_b32_e32 v33, v2
	v_mov_b32_e32 v42, v2
	v_mov_b32_e32 v43, v2
	v_mov_b32_e32 v44, v2
	v_mov_b32_e32 v45, v2
	v_mov_b32_e32 v46, v2
	v_mov_b32_e32 v47, v2
	v_mov_b32_e32 v48, v2
	v_mov_b32_e32 v49, v2
	v_mov_b32_e32 v58, v2
	v_mov_b32_e32 v59, v2
	v_mov_b32_e32 v60, v2
	v_mov_b32_e32 v61, v2
	v_mov_b32_e32 v62, v2
	v_mov_b32_e32 v63, v2
	v_mov_b32_e32 v64, v2
	v_mov_b32_e32 v65, v2
	v_mov_b32_e32 v66, v2
	v_mov_b32_e32 v67, v2
	v_mov_b32_e32 v68, v2
	v_mov_b32_e32 v69, v2
	v_mov_b32_e32 v70, v2
	v_mov_b32_e32 v71, v2
	v_mov_b32_e32 v72, v2
	v_mov_b32_e32 v73, v2
	v_mov_b32_e32 v82, v2
	v_mov_b32_e32 v83, v2
	v_mov_b32_e32 v84, v2
	v_mov_b32_e32 v85, v2
	v_mov_b32_e32 v86, v2
	v_mov_b32_e32 v87, v2
	v_mov_b32_e32 v88, v2
	v_mov_b32_e32 v89, v2
	v_mov_b32_e32 v114, v2
	v_mov_b32_e32 v115, v2
	v_mov_b32_e32 v116, v2
	v_mov_b32_e32 v117, v2
	v_mov_b32_e32 v118, v2
	v_mov_b32_e32 v119, v2
	v_mov_b32_e32 v120, v2
	v_mov_b32_e32 v121, v2
	v_mov_b32_e32 v130, v2
	v_mov_b32_e32 v131, v2
	v_mov_b32_e32 v132, v2
	v_mov_b32_e32 v133, v2
	v_mov_b32_e32 v134, v2
	v_mov_b32_e32 v135, v2
	v_mov_b32_e32 v136, v2
	v_mov_b32_e32 v137, v2
	v_mov_b32_e32 v74, v2
	v_mov_b32_e32 v75, v2
	v_mov_b32_e32 v76, v2
	v_mov_b32_e32 v77, v2
	v_mov_b32_e32 v78, v2
	v_mov_b32_e32 v79, v2
	v_mov_b32_e32 v80, v2
	v_mov_b32_e32 v81, v2
	v_mov_b32_e32 v106, v2
	v_mov_b32_e32 v107, v2
	v_mov_b32_e32 v108, v2
	v_mov_b32_e32 v109, v2
	v_mov_b32_e32 v110, v2
	v_mov_b32_e32 v111, v2
	v_mov_b32_e32 v112, v2
	v_mov_b32_e32 v113, v2
	v_mov_b32_e32 v122, v2
	v_mov_b32_e32 v123, v2
	v_mov_b32_e32 v124, v2
	v_mov_b32_e32 v125, v2
	v_mov_b32_e32 v126, v2
	v_mov_b32_e32 v127, v2
	v_mov_b32_e32 v128, v2
	v_mov_b32_e32 v129, v2
	v_mov_b32_e32 v138, v2
	v_mov_b32_e32 v139, v2
	v_mov_b32_e32 v140, v2
	v_mov_b32_e32 v141, v2
	v_mov_b32_e32 v94, v2
	v_mov_b32_e32 v95, v2
	v_mov_b32_e32 v96, v2
	v_mov_b32_e32 v97, v2
	v_readlane_b32 s69, v254, 5
	v_readlane_b32 s70, v254, 6
	v_readlane_b32 s71, v254, 7
	v_add_u32_e32 v218, 0x18000, v183
	v_add_u32_e32 v219, 0x1c000, v183
.LBB0_574:
	ds_read_b128 v[90:93], v1
	ds_read_b128 v[98:101], v1 offset:1024
	ds_read_b128 v[102:105], v1 offset:2048
	ds_read_b128 v[142:145], v1 offset:3072
	ds_read_b128 v[146:149], v203
	ds_read_b128 v[150:153], v203 offset:1024
	ds_read_b128 v[154:157], v203 offset:2048
	ds_read_b128 v[158:161], v203 offset:3072
	s_add_u32 s24, s22, 0xfffe0080
	s_addc_u32 s25, s23, -1
	s_cmp_eq_u32 s66, 4
	s_cselect_b32 s27, s13, s25
	s_cselect_b32 s26, s46, s24
	s_cselect_b32 s25, s11, s57
	s_cselect_b32 s24, s47, s56
	s_add_i32 m0, s19, 0xc000
	ds_read_b128 v[162:165], v205
	ds_read_b128 v[166:169], v205 offset:1024
	ds_read_b128 v[170:173], v205 offset:2048
	ds_read_b128 v[174:177], v205 offset:3072
	ds_read_b128 v[178:181], v205 offset:4096
	ds_read_b128 v[206:209], v205 offset:5120
	ds_read_b128 v[210:213], v205 offset:6144
	ds_read_b128 v[214:217], v205 offset:7168
	global_load_lds_dwordx4 v190, s[22:23]
	s_add_i32 m0, s19, 0xe000
	s_nop 0
	global_load_lds_dwordx4 v192, s[22:23]
	s_waitcnt vmcnt(8)
	s_waitcnt lgkmcnt(0)
	s_barrier
	s_setprio 1
	s_waitcnt lgkmcnt(0)
	v_mfma_i32_16x16x64_i8 v[94:97], v[90:93], v[162:165], v[94:97]
	v_mfma_i32_16x16x64_i8 v[138:141], v[102:105], v[162:165], v[138:141]
	v_mfma_i32_16x16x64_i8 v[126:129], v[90:93], v[170:173], v[126:129]
	v_mfma_i32_16x16x64_i8 v[122:125], v[102:105], v[170:173], v[122:125]
	v_mfma_i32_16x16x64_i8 v[110:113], v[90:93], v[178:181], v[110:113]
	v_mfma_i32_16x16x64_i8 v[106:109], v[102:105], v[178:181], v[106:109]
	v_mfma_i32_16x16x64_i8 v[78:81], v[90:93], v[210:213], v[78:81]
	v_mfma_i32_16x16x64_i8 v[74:77], v[102:105], v[210:213], v[74:77]
	v_mfma_i32_16x16x64_i8 v[94:97], v[98:101], v[166:169], v[94:97]
	v_mfma_i32_16x16x64_i8 v[138:141], v[142:145], v[166:169], v[138:141]
	v_mfma_i32_16x16x64_i8 v[126:129], v[98:101], v[174:177], v[126:129]
	v_mfma_i32_16x16x64_i8 v[122:125], v[142:145], v[174:177], v[122:125]
	v_mfma_i32_16x16x64_i8 v[110:113], v[98:101], v[206:209], v[110:113]
	v_mfma_i32_16x16x64_i8 v[106:109], v[142:145], v[206:209], v[106:109]
	v_mfma_i32_16x16x64_i8 v[78:81], v[98:101], v[214:217], v[78:81]
	v_mfma_i32_16x16x64_i8 v[74:77], v[142:145], v[214:217], v[74:77]
	s_setprio 0
	s_setprio 1
	v_mfma_i32_16x16x64_i8 v[134:137], v[146:149], v[162:165], v[134:137]
	v_mfma_i32_16x16x64_i8 v[130:133], v[154:157], v[162:165], v[130:133]
	v_mfma_i32_16x16x64_i8 v[118:121], v[146:149], v[170:173], v[118:121]
	v_mfma_i32_16x16x64_i8 v[114:117], v[154:157], v[170:173], v[114:117]
	v_mfma_i32_16x16x64_i8 v[86:89], v[146:149], v[178:181], v[86:89]
	v_mfma_i32_16x16x64_i8 v[82:85], v[154:157], v[178:181], v[82:85]
	v_mfma_i32_16x16x64_i8 v[70:73], v[146:149], v[210:213], v[70:73]
	v_mfma_i32_16x16x64_i8 v[66:69], v[154:157], v[210:213], v[66:69]
	v_mfma_i32_16x16x64_i8 v[134:137], v[150:153], v[166:169], v[134:137]
	v_mfma_i32_16x16x64_i8 v[130:133], v[158:161], v[166:169], v[130:133]
	v_mfma_i32_16x16x64_i8 v[118:121], v[150:153], v[174:177], v[118:121]
	v_mfma_i32_16x16x64_i8 v[114:117], v[158:161], v[174:177], v[114:117]
	v_mfma_i32_16x16x64_i8 v[86:89], v[150:153], v[206:209], v[86:89]
	v_mfma_i32_16x16x64_i8 v[82:85], v[158:161], v[206:209], v[82:85]
	v_mfma_i32_16x16x64_i8 v[70:73], v[150:153], v[214:217], v[70:73]
	v_mfma_i32_16x16x64_i8 v[66:69], v[158:161], v[214:217], v[66:69]
	s_setprio 0
	s_barrier
	s_add_i32 s67, s41, s29
	s_mov_b32 m0, s67
	ds_read_b128 v[162:165], v205 offset:16384
	ds_read_b128 v[166:169], v205 offset:17408
	ds_read_b128 v[170:173], v205 offset:18432
	ds_read_b128 v[174:177], v205 offset:19456
	ds_read_b128 v[178:181], v205 offset:20480
	ds_read_b128 v[206:209], v205 offset:21504
	ds_read_b128 v[210:213], v205 offset:22528
	ds_read_b128 v[214:217], v205 offset:23552
	global_load_lds_dwordx4 v184, s[24:25]
	s_add_i32 m0, s67, 0x2000
	s_add_u32 s68, s24, 0x20000
	s_addc_u32 s69, s25, 0
	s_add_i32 s67, s42, s29
	global_load_lds_dwordx4 v186, s[24:25]
	s_mov_b32 m0, s67
	s_nop 0
	global_load_lds_dwordx4 v184, s[68:69]
	s_add_i32 m0, s67, 0x2000
	s_nop 0
	global_load_lds_dwordx4 v186, s[68:69]
	s_mov_b32 m0, s19
	s_nop 0
	global_load_lds_dwordx4 v184, s[26:27]
	s_mov_b32 m0, s34
	s_nop 0
	global_load_lds_dwordx4 v186, s[26:27]
	s_waitcnt vmcnt(8)
	s_waitcnt lgkmcnt(0)
	s_barrier
	s_setprio 1
	s_waitcnt lgkmcnt(0)
	v_mfma_i32_16x16x64_i8 v[62:65], v[90:93], v[162:165], v[62:65]
	v_mfma_i32_16x16x64_i8 v[58:61], v[102:105], v[162:165], v[58:61]
	v_mfma_i32_16x16x64_i8 v[46:49], v[90:93], v[170:173], v[46:49]
	v_mfma_i32_16x16x64_i8 v[42:45], v[102:105], v[170:173], v[42:45]
	v_mfma_i32_16x16x64_i8 v[30:33], v[90:93], v[178:181], v[30:33]
	v_mfma_i32_16x16x64_i8 v[26:29], v[102:105], v[178:181], v[26:29]
	v_mfma_i32_16x16x64_i8 v[14:17], v[90:93], v[210:213], v[14:17]
	v_mfma_i32_16x16x64_i8 v[10:13], v[102:105], v[210:213], v[10:13]
	v_mfma_i32_16x16x64_i8 v[62:65], v[98:101], v[166:169], v[62:65]
	v_mfma_i32_16x16x64_i8 v[58:61], v[142:145], v[166:169], v[58:61]
	v_mfma_i32_16x16x64_i8 v[46:49], v[98:101], v[174:177], v[46:49]
	v_mfma_i32_16x16x64_i8 v[42:45], v[142:145], v[174:177], v[42:45]
	v_mfma_i32_16x16x64_i8 v[30:33], v[98:101], v[206:209], v[30:33]
	v_mfma_i32_16x16x64_i8 v[26:29], v[142:145], v[206:209], v[26:29]
	v_mfma_i32_16x16x64_i8 v[14:17], v[98:101], v[214:217], v[14:17]
	v_mfma_i32_16x16x64_i8 v[10:13], v[142:145], v[214:217], v[10:13]
	s_setprio 0
	s_setprio 1
	v_mfma_i32_16x16x64_i8 v[54:57], v[146:149], v[162:165], v[54:57]
	v_mfma_i32_16x16x64_i8 v[50:53], v[154:157], v[162:165], v[50:53]
	v_mfma_i32_16x16x64_i8 v[38:41], v[146:149], v[170:173], v[38:41]
	v_mfma_i32_16x16x64_i8 v[34:37], v[154:157], v[170:173], v[34:37]
	v_mfma_i32_16x16x64_i8 v[22:25], v[146:149], v[178:181], v[22:25]
	v_mfma_i32_16x16x64_i8 v[18:21], v[154:157], v[178:181], v[18:21]
	v_mfma_i32_16x16x64_i8 v[6:9], v[146:149], v[210:213], v[6:9]
	v_mfma_i32_16x16x64_i8 v[2:5], v[154:157], v[210:213], v[2:5]
	v_mfma_i32_16x16x64_i8 v[54:57], v[150:153], v[166:169], v[54:57]
	v_mfma_i32_16x16x64_i8 v[50:53], v[158:161], v[166:169], v[50:53]
	v_mfma_i32_16x16x64_i8 v[38:41], v[150:153], v[174:177], v[38:41]
	v_mfma_i32_16x16x64_i8 v[34:37], v[158:161], v[174:177], v[34:37]
	v_mfma_i32_16x16x64_i8 v[22:25], v[150:153], v[206:209], v[22:25]
	v_mfma_i32_16x16x64_i8 v[18:21], v[158:161], v[206:209], v[18:21]
	v_mfma_i32_16x16x64_i8 v[6:9], v[150:153], v[214:217], v[6:9]
	v_mfma_i32_16x16x64_i8 v[2:5], v[158:161], v[214:217], v[2:5]
	s_setprio 0
	s_barrier
	s_add_i32 s67, 0, 0x18000
	s_add_i32 s68, 0, 0x1c000
	ds_read_b128 v[90:93], v218
	ds_read_b128 v[98:101], v218 offset:1024
	ds_read_b128 v[102:105], v218 offset:2048
	ds_read_b128 v[142:145], v218 offset:3072
	ds_read_b128 v[146:149], v219
	ds_read_b128 v[150:153], v219 offset:1024
	ds_read_b128 v[154:157], v219 offset:2048
	ds_read_b128 v[158:161], v219 offset:3072
	s_add_u32 s26, s26, 0x20000
	s_addc_u32 s27, s27, 0
	s_mov_b32 m0, s35
	ds_read_b128 v[162:165], v205 offset:32768
	ds_read_b128 v[166:169], v205 offset:33792
	ds_read_b128 v[170:173], v205 offset:34816
	ds_read_b128 v[174:177], v205 offset:35840
	ds_read_b128 v[178:181], v205 offset:36864
	ds_read_b128 v[206:209], v205 offset:37888
	ds_read_b128 v[210:213], v205 offset:38912
	ds_read_b128 v[214:217], v205 offset:39936
	global_load_lds_dwordx4 v184, s[26:27]
	s_mov_b32 m0, s36
	s_nop 0
	global_load_lds_dwordx4 v186, s[26:27]
	s_waitcnt vmcnt(8)
	s_waitcnt lgkmcnt(0)
	s_barrier
	s_setprio 1
	s_waitcnt lgkmcnt(0)
	v_mfma_i32_16x16x64_i8 v[94:97], v[90:93], v[162:165], v[94:97]
	v_mfma_i32_16x16x64_i8 v[138:141], v[102:105], v[162:165], v[138:141]
	v_mfma_i32_16x16x64_i8 v[126:129], v[90:93], v[170:173], v[126:129]
	v_mfma_i32_16x16x64_i8 v[122:125], v[102:105], v[170:173], v[122:125]
	v_mfma_i32_16x16x64_i8 v[110:113], v[90:93], v[178:181], v[110:113]
	v_mfma_i32_16x16x64_i8 v[106:109], v[102:105], v[178:181], v[106:109]
	v_mfma_i32_16x16x64_i8 v[78:81], v[90:93], v[210:213], v[78:81]
	v_mfma_i32_16x16x64_i8 v[74:77], v[102:105], v[210:213], v[74:77]
	v_mfma_i32_16x16x64_i8 v[94:97], v[98:101], v[166:169], v[94:97]
	v_mfma_i32_16x16x64_i8 v[138:141], v[142:145], v[166:169], v[138:141]
	v_mfma_i32_16x16x64_i8 v[126:129], v[98:101], v[174:177], v[126:129]
	v_mfma_i32_16x16x64_i8 v[122:125], v[142:145], v[174:177], v[122:125]
	v_mfma_i32_16x16x64_i8 v[110:113], v[98:101], v[206:209], v[110:113]
	v_mfma_i32_16x16x64_i8 v[106:109], v[142:145], v[206:209], v[106:109]
	v_mfma_i32_16x16x64_i8 v[78:81], v[98:101], v[214:217], v[78:81]
	v_mfma_i32_16x16x64_i8 v[74:77], v[142:145], v[214:217], v[74:77]
	s_setprio 0
	s_setprio 1
	v_mfma_i32_16x16x64_i8 v[134:137], v[146:149], v[162:165], v[134:137]
	v_mfma_i32_16x16x64_i8 v[130:133], v[154:157], v[162:165], v[130:133]
	v_mfma_i32_16x16x64_i8 v[118:121], v[146:149], v[170:173], v[118:121]
	v_mfma_i32_16x16x64_i8 v[114:117], v[154:157], v[170:173], v[114:117]
	v_mfma_i32_16x16x64_i8 v[86:89], v[146:149], v[178:181], v[86:89]
	v_mfma_i32_16x16x64_i8 v[82:85], v[154:157], v[178:181], v[82:85]
	v_mfma_i32_16x16x64_i8 v[70:73], v[146:149], v[210:213], v[70:73]
	v_mfma_i32_16x16x64_i8 v[66:69], v[154:157], v[210:213], v[66:69]
	v_mfma_i32_16x16x64_i8 v[134:137], v[150:153], v[166:169], v[134:137]
	v_mfma_i32_16x16x64_i8 v[130:133], v[158:161], v[166:169], v[130:133]
	v_mfma_i32_16x16x64_i8 v[118:121], v[150:153], v[174:177], v[118:121]
	v_mfma_i32_16x16x64_i8 v[114:117], v[158:161], v[174:177], v[114:117]
	v_mfma_i32_16x16x64_i8 v[86:89], v[150:153], v[206:209], v[86:89]
	v_mfma_i32_16x16x64_i8 v[82:85], v[158:161], v[206:209], v[82:85]
	v_mfma_i32_16x16x64_i8 v[70:73], v[150:153], v[214:217], v[70:73]
	v_mfma_i32_16x16x64_i8 v[66:69], v[158:161], v[214:217], v[66:69]
	s_setprio 0
	s_barrier
	s_add_u32 s98, s26, 0xfffe0080
	s_addc_u32 s99, s27, -1
	s_add_i32 s26, s67, s29
	s_mov_b32 m0, s26
	ds_read_b128 v[162:165], v205 offset:49152
	ds_read_b128 v[166:169], v205 offset:50176
	ds_read_b128 v[170:173], v205 offset:51200
	ds_read_b128 v[174:177], v205 offset:52224
	ds_read_b128 v[178:181], v205 offset:53248
	ds_read_b128 v[206:209], v205 offset:54272
	ds_read_b128 v[210:213], v205 offset:55296
	ds_read_b128 v[214:217], v205 offset:56320
	s_add_u32 s100, s24, 0x80
	s_addc_u32 s101, s25, 0
	global_load_lds_dwordx4 v184, s[100:101]
	s_add_i32 m0, s26, 0x2000
	s_add_u32 s24, s24, 0x20080
	s_addc_u32 s25, s25, 0
	s_add_i32 s26, s68, s29
	global_load_lds_dwordx4 v186, s[100:101]
	s_mov_b32 m0, s26
	s_nop 0
	global_load_lds_dwordx4 v184, s[24:25]
	s_add_i32 m0, s26, 0x2000
	s_nop 0
	global_load_lds_dwordx4 v186, s[24:25]
	s_mov_b32 m0, s38
	s_nop 0
	global_load_lds_dwordx4 v184, s[98:99]
	s_mov_b32 m0, s39
	s_nop 0
	global_load_lds_dwordx4 v186, s[98:99]
	s_waitcnt vmcnt(8)
	s_waitcnt lgkmcnt(0)
	s_barrier
	s_setprio 1
	s_waitcnt lgkmcnt(0)
	v_mfma_i32_16x16x64_i8 v[62:65], v[90:93], v[162:165], v[62:65]
	v_mfma_i32_16x16x64_i8 v[58:61], v[102:105], v[162:165], v[58:61]
	v_mfma_i32_16x16x64_i8 v[46:49], v[90:93], v[170:173], v[46:49]
	v_mfma_i32_16x16x64_i8 v[42:45], v[102:105], v[170:173], v[42:45]
	v_mfma_i32_16x16x64_i8 v[30:33], v[90:93], v[178:181], v[30:33]
	v_mfma_i32_16x16x64_i8 v[26:29], v[102:105], v[178:181], v[26:29]
	v_mfma_i32_16x16x64_i8 v[14:17], v[90:93], v[210:213], v[14:17]
	v_mfma_i32_16x16x64_i8 v[10:13], v[102:105], v[210:213], v[10:13]
	v_mfma_i32_16x16x64_i8 v[62:65], v[98:101], v[166:169], v[62:65]
	v_mfma_i32_16x16x64_i8 v[58:61], v[142:145], v[166:169], v[58:61]
	v_mfma_i32_16x16x64_i8 v[46:49], v[98:101], v[174:177], v[46:49]
	v_mfma_i32_16x16x64_i8 v[42:45], v[142:145], v[174:177], v[42:45]
	v_mfma_i32_16x16x64_i8 v[30:33], v[98:101], v[206:209], v[30:33]
	v_mfma_i32_16x16x64_i8 v[26:29], v[142:145], v[206:209], v[26:29]
	v_mfma_i32_16x16x64_i8 v[14:17], v[98:101], v[214:217], v[14:17]
	v_mfma_i32_16x16x64_i8 v[10:13], v[142:145], v[214:217], v[10:13]
	s_setprio 0
	s_setprio 1
	v_mfma_i32_16x16x64_i8 v[54:57], v[146:149], v[162:165], v[54:57]
	v_mfma_i32_16x16x64_i8 v[50:53], v[154:157], v[162:165], v[50:53]
	v_mfma_i32_16x16x64_i8 v[38:41], v[146:149], v[170:173], v[38:41]
	v_mfma_i32_16x16x64_i8 v[34:37], v[154:157], v[170:173], v[34:37]
	v_mfma_i32_16x16x64_i8 v[22:25], v[146:149], v[178:181], v[22:25]
	v_mfma_i32_16x16x64_i8 v[18:21], v[154:157], v[178:181], v[18:21]
	v_mfma_i32_16x16x64_i8 v[6:9], v[146:149], v[210:213], v[6:9]
	v_mfma_i32_16x16x64_i8 v[2:5], v[154:157], v[210:213], v[2:5]
	v_mfma_i32_16x16x64_i8 v[54:57], v[150:153], v[166:169], v[54:57]
	v_mfma_i32_16x16x64_i8 v[50:53], v[158:161], v[166:169], v[50:53]
	v_mfma_i32_16x16x64_i8 v[38:41], v[150:153], v[174:177], v[38:41]
	v_mfma_i32_16x16x64_i8 v[34:37], v[158:161], v[174:177], v[34:37]
	v_mfma_i32_16x16x64_i8 v[22:25], v[150:153], v[206:209], v[22:25]
	v_mfma_i32_16x16x64_i8 v[18:21], v[158:161], v[206:209], v[18:21]
	v_mfma_i32_16x16x64_i8 v[6:9], v[150:153], v[214:217], v[6:9]
	v_mfma_i32_16x16x64_i8 v[2:5], v[158:161], v[214:217], v[2:5]
	s_setprio 0
	s_barrier
	s_add_i32 s66, s66, 2
	s_add_u32 s22, s22, 0x100
	s_addc_u32 s23, s23, 0
	s_add_u32 s56, s56, 0x100
	s_addc_u32 s57, s57, 0
	s_cmp_gt_u32 s66, 5
	s_cbranch_scc0 .LBB0_574
	s_and_b64 vcc, exec, s[8:9]
	s_cbranch_vccz .LBB0_577
	s_barrier

.LBB0_708:
	s_ashr_i32 s27, s26, 31
	s_lshl_b64 s[28:29], s[26:27], 20
	s_add_u32 s28, s50, s28
	s_addc_u32 s29, s51, s29
	s_and_b64 s[30:31], s[2:3], exec
	s_cselect_b32 s27, s29, s37
	s_cselect_b32 s74, s28, s36
	s_ashr_i32 s25, s24, 31
	s_lshl_b64 s[30:31], s[24:25], 20
	s_add_u32 s30, s84, s30
	s_addc_u32 s31, s86, s31
	s_and_b64 s[40:41], s[2:3], exec
	s_cselect_b32 s25, s31, s39
	s_cselect_b32 s75, s30, s38
	s_add_u32 s36, s36, 0x80080
	s_addc_u32 s37, s37, 0
	s_add_u32 s76, s38, 0x100
	v_mov_b32_e32 v2, 0
	s_addc_u32 s77, s39, 0
	s_mov_b32 s78, -2
	v_mov_b32_e32 v3, v2
	v_mov_b32_e32 v4, v2
	v_mov_b32_e32 v5, v2
	v_mov_b32_e32 v6, v2
	v_mov_b32_e32 v7, v2
	v_mov_b32_e32 v8, v2
	v_mov_b32_e32 v9, v2
	v_mov_b32_e32 v14, v2
	v_mov_b32_e32 v15, v2
	v_mov_b32_e32 v16, v2
	v_mov_b32_e32 v17, v2
	v_mov_b32_e32 v22, v2
	v_mov_b32_e32 v23, v2
	v_mov_b32_e32 v24, v2
	v_mov_b32_e32 v25, v2
	v_mov_b32_e32 v30, v2
	v_mov_b32_e32 v31, v2
	v_mov_b32_e32 v32, v2
	v_mov_b32_e32 v33, v2
	v_mov_b32_e32 v38, v2
	v_mov_b32_e32 v39, v2
	v_mov_b32_e32 v40, v2
	v_mov_b32_e32 v41, v2
	v_mov_b32_e32 v46, v2
	v_mov_b32_e32 v47, v2
	v_mov_b32_e32 v48, v2
	v_mov_b32_e32 v49, v2
	v_mov_b32_e32 v54, v2
	v_mov_b32_e32 v55, v2
	v_mov_b32_e32 v56, v2
	v_mov_b32_e32 v57, v2
	v_mov_b32_e32 v10, v2
	v_mov_b32_e32 v11, v2
	v_mov_b32_e32 v12, v2
	v_mov_b32_e32 v13, v2
	v_mov_b32_e32 v18, v2
	v_mov_b32_e32 v19, v2
	v_mov_b32_e32 v20, v2
	v_mov_b32_e32 v21, v2
	v_mov_b32_e32 v26, v2
	v_mov_b32_e32 v27, v2
	v_mov_b32_e32 v28, v2
	v_mov_b32_e32 v29, v2
	v_mov_b32_e32 v34, v2
	v_mov_b32_e32 v35, v2
	v_mov_b32_e32 v36, v2
	v_mov_b32_e32 v37, v2
	v_mov_b32_e32 v42, v2
	v_mov_b32_e32 v43, v2
	v_mov_b32_e32 v44, v2
	v_mov_b32_e32 v45, v2
	v_mov_b32_e32 v50, v2
	v_mov_b32_e32 v51, v2
	v_mov_b32_e32 v52, v2
	v_mov_b32_e32 v53, v2
	v_mov_b32_e32 v58, v2
	v_mov_b32_e32 v59, v2
	v_mov_b32_e32 v60, v2
	v_mov_b32_e32 v61, v2
	v_mov_b32_e32 v62, v2
	v_mov_b32_e32 v63, v2
	v_mov_b32_e32 v64, v2
	v_mov_b32_e32 v65, v2
	v_mov_b32_e32 v66, v2
	v_mov_b32_e32 v67, v2
	v_mov_b32_e32 v68, v2
	v_mov_b32_e32 v69, v2
	v_mov_b32_e32 v70, v2
	v_mov_b32_e32 v71, v2
	v_mov_b32_e32 v72, v2
	v_mov_b32_e32 v73, v2
	v_mov_b32_e32 v82, v2
	v_mov_b32_e32 v83, v2
	v_mov_b32_e32 v84, v2
	v_mov_b32_e32 v85, v2
	v_mov_b32_e32 v86, v2
	v_mov_b32_e32 v87, v2
	v_mov_b32_e32 v88, v2
	v_mov_b32_e32 v89, v2
	v_mov_b32_e32 v98, v2
	v_mov_b32_e32 v99, v2
	v_mov_b32_e32 v100, v2
	v_mov_b32_e32 v101, v2
	v_mov_b32_e32 v102, v2
	v_mov_b32_e32 v103, v2
	v_mov_b32_e32 v104, v2
	v_mov_b32_e32 v105, v2
	v_mov_b32_e32 v114, v2
	v_mov_b32_e32 v115, v2
	v_mov_b32_e32 v116, v2
	v_mov_b32_e32 v117, v2
	v_mov_b32_e32 v118, v2
	v_mov_b32_e32 v119, v2
	v_mov_b32_e32 v120, v2
	v_mov_b32_e32 v121, v2
	v_mov_b32_e32 v74, v2
	v_mov_b32_e32 v75, v2
	v_mov_b32_e32 v76, v2
	v_mov_b32_e32 v77, v2
	v_mov_b32_e32 v78, v2
	v_mov_b32_e32 v79, v2
	v_mov_b32_e32 v80, v2
	v_mov_b32_e32 v81, v2
	v_mov_b32_e32 v90, v2
	v_mov_b32_e32 v91, v2
	v_mov_b32_e32 v92, v2
	v_mov_b32_e32 v93, v2
	v_mov_b32_e32 v94, v2
	v_mov_b32_e32 v95, v2
	v_mov_b32_e32 v96, v2
	v_mov_b32_e32 v97, v2
	v_mov_b32_e32 v106, v2
	v_mov_b32_e32 v107, v2
	v_mov_b32_e32 v108, v2
	v_mov_b32_e32 v109, v2
	v_mov_b32_e32 v110, v2
	v_mov_b32_e32 v111, v2
	v_mov_b32_e32 v112, v2
	v_mov_b32_e32 v113, v2
	v_mov_b32_e32 v122, v2
	v_mov_b32_e32 v123, v2
	v_mov_b32_e32 v124, v2
	v_mov_b32_e32 v125, v2
	v_mov_b32_e32 v126, v2
	v_mov_b32_e32 v127, v2
	v_mov_b32_e32 v128, v2
	v_mov_b32_e32 v129, v2
	v_add_u32_e32 v216, 0x18000, v176
	v_add_u32_e32 v217, 0x1c000, v176
.LBB0_709:
	ds_read_b128 v[130:133], v178
	ds_read_b128 v[134:137], v178 offset:1024
	ds_read_b128 v[138:141], v178 offset:2048
	ds_read_b128 v[142:145], v178 offset:3072
	ds_read_b128 v[146:149], v179
	ds_read_b128 v[150:153], v179 offset:1024
	ds_read_b128 v[154:157], v179 offset:2048
	ds_read_b128 v[158:161], v179 offset:3072
	s_add_u32 s38, s36, 0xfff80080
	s_addc_u32 s39, s37, -1
	s_cmp_eq_u32 s78, 28
	s_cselect_b32 s41, s27, s39
	s_cselect_b32 s40, s74, s38
	s_cselect_b32 s39, s25, s77
	s_cselect_b32 s38, s75, s76
	s_add_i32 m0, s35, 0xc000
	ds_read_b128 v[184:187], v180
	ds_read_b128 v[188:191], v180 offset:1024
	ds_read_b128 v[192:195], v180 offset:2048
	ds_read_b128 v[196:199], v180 offset:3072
	ds_read_b128 v[200:203], v180 offset:4096
	ds_read_b128 v[204:207], v180 offset:5120
	ds_read_b128 v[208:211], v180 offset:6144
	ds_read_b128 v[212:215], v180 offset:7168
	global_load_lds_dwordx4 v168, s[36:37]
	s_add_i32 m0, s35, 0xe000
	s_nop 0
	global_load_lds_dwordx4 v170, s[36:37]
	s_waitcnt vmcnt(8)
	s_waitcnt lgkmcnt(0)
	s_barrier
	s_setprio 1
	s_waitcnt lgkmcnt(0)
	v_mfma_i32_16x16x64_i8 v[126:129], v[130:133], v[184:187], v[126:129]
	v_mfma_i32_16x16x64_i8 v[122:125], v[138:141], v[184:187], v[122:125]
	v_mfma_i32_16x16x64_i8 v[110:113], v[130:133], v[192:195], v[110:113]
	v_mfma_i32_16x16x64_i8 v[106:109], v[138:141], v[192:195], v[106:109]
	v_mfma_i32_16x16x64_i8 v[94:97], v[130:133], v[200:203], v[94:97]
	v_mfma_i32_16x16x64_i8 v[90:93], v[138:141], v[200:203], v[90:93]
	v_mfma_i32_16x16x64_i8 v[78:81], v[130:133], v[208:211], v[78:81]
	v_mfma_i32_16x16x64_i8 v[74:77], v[138:141], v[208:211], v[74:77]
	v_mfma_i32_16x16x64_i8 v[126:129], v[134:137], v[188:191], v[126:129]
	v_mfma_i32_16x16x64_i8 v[122:125], v[142:145], v[188:191], v[122:125]
	v_mfma_i32_16x16x64_i8 v[110:113], v[134:137], v[196:199], v[110:113]
	v_mfma_i32_16x16x64_i8 v[106:109], v[142:145], v[196:199], v[106:109]
	v_mfma_i32_16x16x64_i8 v[94:97], v[134:137], v[204:207], v[94:97]
	v_mfma_i32_16x16x64_i8 v[90:93], v[142:145], v[204:207], v[90:93]
	v_mfma_i32_16x16x64_i8 v[78:81], v[134:137], v[212:215], v[78:81]
	v_mfma_i32_16x16x64_i8 v[74:77], v[142:145], v[212:215], v[74:77]
	s_setprio 0
	s_setprio 1
	v_mfma_i32_16x16x64_i8 v[118:121], v[146:149], v[184:187], v[118:121]
	v_mfma_i32_16x16x64_i8 v[114:117], v[154:157], v[184:187], v[114:117]
	v_mfma_i32_16x16x64_i8 v[102:105], v[146:149], v[192:195], v[102:105]
	v_mfma_i32_16x16x64_i8 v[98:101], v[154:157], v[192:195], v[98:101]
	v_mfma_i32_16x16x64_i8 v[86:89], v[146:149], v[200:203], v[86:89]
	v_mfma_i32_16x16x64_i8 v[82:85], v[154:157], v[200:203], v[82:85]
	v_mfma_i32_16x16x64_i8 v[70:73], v[146:149], v[208:211], v[70:73]
	v_mfma_i32_16x16x64_i8 v[66:69], v[154:157], v[208:211], v[66:69]
	v_mfma_i32_16x16x64_i8 v[118:121], v[150:153], v[188:191], v[118:121]
	v_mfma_i32_16x16x64_i8 v[114:117], v[158:161], v[188:191], v[114:117]
	v_mfma_i32_16x16x64_i8 v[102:105], v[150:153], v[196:199], v[102:105]
	v_mfma_i32_16x16x64_i8 v[98:101], v[158:161], v[196:199], v[98:101]
	v_mfma_i32_16x16x64_i8 v[86:89], v[150:153], v[204:207], v[86:89]
	v_mfma_i32_16x16x64_i8 v[82:85], v[158:161], v[204:207], v[82:85]
	v_mfma_i32_16x16x64_i8 v[70:73], v[150:153], v[212:215], v[70:73]
	v_mfma_i32_16x16x64_i8 v[66:69], v[158:161], v[212:215], v[66:69]
	s_setprio 0
	s_barrier
	s_add_i32 s79, s0, s42
	s_mov_b32 m0, s79
	ds_read_b128 v[184:187], v180 offset:16384
	ds_read_b128 v[188:191], v180 offset:17408
	ds_read_b128 v[192:195], v180 offset:18432
	ds_read_b128 v[196:199], v180 offset:19456
	ds_read_b128 v[200:203], v180 offset:20480
	ds_read_b128 v[204:207], v180 offset:21504
	ds_read_b128 v[208:211], v180 offset:22528
	ds_read_b128 v[212:215], v180 offset:23552
	global_load_lds_dwordx4 v162, s[38:39]
	s_add_i32 m0, s79, 0x2000
	s_add_u32 s82, s38, 0x80000
	s_addc_u32 s83, s39, 0
	s_add_i32 s79, s68, s42
	global_load_lds_dwordx4 v164, s[38:39]
	s_mov_b32 m0, s79
	s_nop 0
	global_load_lds_dwordx4 v162, s[82:83]
	s_add_i32 m0, s79, 0x2000
	s_nop 0
	global_load_lds_dwordx4 v164, s[82:83]
	s_mov_b32 m0, s35
	s_nop 0
	global_load_lds_dwordx4 v162, s[40:41]
	s_mov_b32 m0, s46
	s_nop 0
	global_load_lds_dwordx4 v164, s[40:41]
	s_waitcnt vmcnt(8)
	s_waitcnt lgkmcnt(0)
	s_barrier
	s_setprio 1
	s_waitcnt lgkmcnt(0)
	v_mfma_i32_16x16x64_i8 v[62:65], v[130:133], v[184:187], v[62:65]
	v_mfma_i32_16x16x64_i8 v[58:61], v[138:141], v[184:187], v[58:61]
	v_mfma_i32_16x16x64_i8 v[50:53], v[130:133], v[192:195], v[50:53]
	v_mfma_i32_16x16x64_i8 v[42:45], v[138:141], v[192:195], v[42:45]
	v_mfma_i32_16x16x64_i8 v[34:37], v[130:133], v[200:203], v[34:37]
	v_mfma_i32_16x16x64_i8 v[26:29], v[138:141], v[200:203], v[26:29]
	v_mfma_i32_16x16x64_i8 v[18:21], v[130:133], v[208:211], v[18:21]
	v_mfma_i32_16x16x64_i8 v[10:13], v[138:141], v[208:211], v[10:13]
	v_mfma_i32_16x16x64_i8 v[62:65], v[134:137], v[188:191], v[62:65]
	v_mfma_i32_16x16x64_i8 v[58:61], v[142:145], v[188:191], v[58:61]
	v_mfma_i32_16x16x64_i8 v[50:53], v[134:137], v[196:199], v[50:53]
	v_mfma_i32_16x16x64_i8 v[42:45], v[142:145], v[196:199], v[42:45]
	v_mfma_i32_16x16x64_i8 v[34:37], v[134:137], v[204:207], v[34:37]
	v_mfma_i32_16x16x64_i8 v[26:29], v[142:145], v[204:207], v[26:29]
	v_mfma_i32_16x16x64_i8 v[18:21], v[134:137], v[212:215], v[18:21]
	v_mfma_i32_16x16x64_i8 v[10:13], v[142:145], v[212:215], v[10:13]
	s_setprio 0
	s_setprio 1
	v_mfma_i32_16x16x64_i8 v[54:57], v[146:149], v[184:187], v[54:57]
	v_mfma_i32_16x16x64_i8 v[46:49], v[154:157], v[184:187], v[46:49]
	v_mfma_i32_16x16x64_i8 v[38:41], v[146:149], v[192:195], v[38:41]
	v_mfma_i32_16x16x64_i8 v[30:33], v[154:157], v[192:195], v[30:33]
	v_mfma_i32_16x16x64_i8 v[22:25], v[146:149], v[200:203], v[22:25]
	v_mfma_i32_16x16x64_i8 v[14:17], v[154:157], v[200:203], v[14:17]
	v_mfma_i32_16x16x64_i8 v[6:9], v[146:149], v[208:211], v[6:9]
	v_mfma_i32_16x16x64_i8 v[2:5], v[154:157], v[208:211], v[2:5]
	v_mfma_i32_16x16x64_i8 v[54:57], v[150:153], v[188:191], v[54:57]
	v_mfma_i32_16x16x64_i8 v[46:49], v[158:161], v[188:191], v[46:49]
	v_mfma_i32_16x16x64_i8 v[38:41], v[150:153], v[196:199], v[38:41]
	v_mfma_i32_16x16x64_i8 v[30:33], v[158:161], v[196:199], v[30:33]
	v_mfma_i32_16x16x64_i8 v[22:25], v[150:153], v[204:207], v[22:25]
	v_mfma_i32_16x16x64_i8 v[14:17], v[158:161], v[204:207], v[14:17]
	v_mfma_i32_16x16x64_i8 v[6:9], v[150:153], v[212:215], v[6:9]
	v_mfma_i32_16x16x64_i8 v[2:5], v[158:161], v[212:215], v[2:5]
	s_setprio 0
	s_barrier
	s_add_i32 s79, 0, 0x18000
	s_add_i32 s80, 0, 0x1c000
	ds_read_b128 v[130:133], v216
	ds_read_b128 v[134:137], v216 offset:1024
	ds_read_b128 v[138:141], v216 offset:2048
	ds_read_b128 v[142:145], v216 offset:3072
	ds_read_b128 v[146:149], v217
	ds_read_b128 v[150:153], v217 offset:1024
	ds_read_b128 v[154:157], v217 offset:2048
	ds_read_b128 v[158:161], v217 offset:3072
	s_add_u32 s40, s40, 0x80000
	s_addc_u32 s41, s41, 0
	s_mov_b32 m0, s47
	ds_read_b128 v[184:187], v180 offset:32768
	ds_read_b128 v[188:191], v180 offset:33792
	ds_read_b128 v[192:195], v180 offset:34816
	ds_read_b128 v[196:199], v180 offset:35840
	ds_read_b128 v[200:203], v180 offset:36864
	ds_read_b128 v[204:207], v180 offset:37888
	ds_read_b128 v[208:211], v180 offset:38912
	ds_read_b128 v[212:215], v180 offset:39936
	global_load_lds_dwordx4 v162, s[40:41]
	s_mov_b32 m0, s54
	s_nop 0
	global_load_lds_dwordx4 v164, s[40:41]
	s_waitcnt vmcnt(8)
	s_waitcnt lgkmcnt(0)
	s_barrier
	s_setprio 1
	s_waitcnt lgkmcnt(0)
	v_mfma_i32_16x16x64_i8 v[126:129], v[130:133], v[184:187], v[126:129]
	v_mfma_i32_16x16x64_i8 v[122:125], v[138:141], v[184:187], v[122:125]
	v_mfma_i32_16x16x64_i8 v[110:113], v[130:133], v[192:195], v[110:113]
	v_mfma_i32_16x16x64_i8 v[106:109], v[138:141], v[192:195], v[106:109]
	v_mfma_i32_16x16x64_i8 v[94:97], v[130:133], v[200:203], v[94:97]
	v_mfma_i32_16x16x64_i8 v[90:93], v[138:141], v[200:203], v[90:93]
	v_mfma_i32_16x16x64_i8 v[78:81], v[130:133], v[208:211], v[78:81]
	v_mfma_i32_16x16x64_i8 v[74:77], v[138:141], v[208:211], v[74:77]
	v_mfma_i32_16x16x64_i8 v[126:129], v[134:137], v[188:191], v[126:129]
	v_mfma_i32_16x16x64_i8 v[122:125], v[142:145], v[188:191], v[122:125]
	v_mfma_i32_16x16x64_i8 v[110:113], v[134:137], v[196:199], v[110:113]
	v_mfma_i32_16x16x64_i8 v[106:109], v[142:145], v[196:199], v[106:109]
	v_mfma_i32_16x16x64_i8 v[94:97], v[134:137], v[204:207], v[94:97]
	v_mfma_i32_16x16x64_i8 v[90:93], v[142:145], v[204:207], v[90:93]
	v_mfma_i32_16x16x64_i8 v[78:81], v[134:137], v[212:215], v[78:81]
	v_mfma_i32_16x16x64_i8 v[74:77], v[142:145], v[212:215], v[74:77]
	s_setprio 0
	s_setprio 1
	v_mfma_i32_16x16x64_i8 v[118:121], v[146:149], v[184:187], v[118:121]
	v_mfma_i32_16x16x64_i8 v[114:117], v[154:157], v[184:187], v[114:117]
	v_mfma_i32_16x16x64_i8 v[102:105], v[146:149], v[192:195], v[102:105]
	v_mfma_i32_16x16x64_i8 v[98:101], v[154:157], v[192:195], v[98:101]
	v_mfma_i32_16x16x64_i8 v[86:89], v[146:149], v[200:203], v[86:89]
	v_mfma_i32_16x16x64_i8 v[82:85], v[154:157], v[200:203], v[82:85]
	v_mfma_i32_16x16x64_i8 v[70:73], v[146:149], v[208:211], v[70:73]
	v_mfma_i32_16x16x64_i8 v[66:69], v[154:157], v[208:211], v[66:69]
	v_mfma_i32_16x16x64_i8 v[118:121], v[150:153], v[188:191], v[118:121]
	v_mfma_i32_16x16x64_i8 v[114:117], v[158:161], v[188:191], v[114:117]
	v_mfma_i32_16x16x64_i8 v[102:105], v[150:153], v[196:199], v[102:105]
	v_mfma_i32_16x16x64_i8 v[98:101], v[158:161], v[196:199], v[98:101]
	v_mfma_i32_16x16x64_i8 v[86:89], v[150:153], v[204:207], v[86:89]
	v_mfma_i32_16x16x64_i8 v[82:85], v[158:161], v[204:207], v[82:85]
	v_mfma_i32_16x16x64_i8 v[70:73], v[150:153], v[212:215], v[70:73]
	v_mfma_i32_16x16x64_i8 v[66:69], v[158:161], v[212:215], v[66:69]
	s_setprio 0
	s_barrier
	s_add_u32 s98, s40, 0xfff80080
	s_addc_u32 s99, s41, -1
	s_add_i32 s40, s79, s42
	s_mov_b32 m0, s40
	ds_read_b128 v[184:187], v180 offset:49152
	ds_read_b128 v[188:191], v180 offset:50176
	ds_read_b128 v[192:195], v180 offset:51200
	ds_read_b128 v[196:199], v180 offset:52224
	ds_read_b128 v[200:203], v180 offset:53248
	ds_read_b128 v[204:207], v180 offset:54272
	ds_read_b128 v[208:211], v180 offset:55296
	ds_read_b128 v[212:215], v180 offset:56320
	s_add_u32 s100, s38, 0x80
	s_addc_u32 s101, s39, 0
	global_load_lds_dwordx4 v162, s[100:101]
	s_add_i32 m0, s40, 0x2000
	s_add_u32 s38, s38, 0x80080
	s_addc_u32 s39, s39, 0
	s_add_i32 s40, s80, s42
	global_load_lds_dwordx4 v164, s[100:101]
	s_mov_b32 m0, s40
	s_nop 0
	global_load_lds_dwordx4 v162, s[38:39]
	s_add_i32 m0, s40, 0x2000
	s_nop 0
	global_load_lds_dwordx4 v164, s[38:39]
	s_mov_b32 m0, s66
	s_nop 0
	global_load_lds_dwordx4 v162, s[98:99]
	s_mov_b32 m0, s67
	s_nop 0
	global_load_lds_dwordx4 v164, s[98:99]
	s_waitcnt vmcnt(8)
	s_waitcnt lgkmcnt(0)
	s_barrier
	s_setprio 1
	s_waitcnt lgkmcnt(0)
	v_mfma_i32_16x16x64_i8 v[62:65], v[130:133], v[184:187], v[62:65]
	v_mfma_i32_16x16x64_i8 v[58:61], v[138:141], v[184:187], v[58:61]
	v_mfma_i32_16x16x64_i8 v[50:53], v[130:133], v[192:195], v[50:53]
	v_mfma_i32_16x16x64_i8 v[42:45], v[138:141], v[192:195], v[42:45]
	v_mfma_i32_16x16x64_i8 v[34:37], v[130:133], v[200:203], v[34:37]
	v_mfma_i32_16x16x64_i8 v[26:29], v[138:141], v[200:203], v[26:29]
	v_mfma_i32_16x16x64_i8 v[18:21], v[130:133], v[208:211], v[18:21]
	v_mfma_i32_16x16x64_i8 v[10:13], v[138:141], v[208:211], v[10:13]
	v_mfma_i32_16x16x64_i8 v[62:65], v[134:137], v[188:191], v[62:65]
	v_mfma_i32_16x16x64_i8 v[58:61], v[142:145], v[188:191], v[58:61]
	v_mfma_i32_16x16x64_i8 v[50:53], v[134:137], v[196:199], v[50:53]
	v_mfma_i32_16x16x64_i8 v[42:45], v[142:145], v[196:199], v[42:45]
	v_mfma_i32_16x16x64_i8 v[34:37], v[134:137], v[204:207], v[34:37]
	v_mfma_i32_16x16x64_i8 v[26:29], v[142:145], v[204:207], v[26:29]
	v_mfma_i32_16x16x64_i8 v[18:21], v[134:137], v[212:215], v[18:21]
	v_mfma_i32_16x16x64_i8 v[10:13], v[142:145], v[212:215], v[10:13]
	s_setprio 0
	s_setprio 1
	v_mfma_i32_16x16x64_i8 v[54:57], v[146:149], v[184:187], v[54:57]
	v_mfma_i32_16x16x64_i8 v[46:49], v[154:157], v[184:187], v[46:49]
	v_mfma_i32_16x16x64_i8 v[38:41], v[146:149], v[192:195], v[38:41]
	v_mfma_i32_16x16x64_i8 v[30:33], v[154:157], v[192:195], v[30:33]
	v_mfma_i32_16x16x64_i8 v[22:25], v[146:149], v[200:203], v[22:25]
	v_mfma_i32_16x16x64_i8 v[14:17], v[154:157], v[200:203], v[14:17]
	v_mfma_i32_16x16x64_i8 v[6:9], v[146:149], v[208:211], v[6:9]
	v_mfma_i32_16x16x64_i8 v[2:5], v[154:157], v[208:211], v[2:5]
	v_mfma_i32_16x16x64_i8 v[54:57], v[150:153], v[188:191], v[54:57]
	v_mfma_i32_16x16x64_i8 v[46:49], v[158:161], v[188:191], v[46:49]
	v_mfma_i32_16x16x64_i8 v[38:41], v[150:153], v[196:199], v[38:41]
	v_mfma_i32_16x16x64_i8 v[30:33], v[158:161], v[196:199], v[30:33]
	v_mfma_i32_16x16x64_i8 v[22:25], v[150:153], v[204:207], v[22:25]
	v_mfma_i32_16x16x64_i8 v[14:17], v[158:161], v[204:207], v[14:17]
	v_mfma_i32_16x16x64_i8 v[6:9], v[150:153], v[212:215], v[6:9]
	v_mfma_i32_16x16x64_i8 v[2:5], v[158:161], v[212:215], v[2:5]
	s_setprio 0
	s_barrier
	s_add_i32 s78, s78, 2
	s_add_u32 s36, s36, 0x100
	s_addc_u32 s37, s37, 0
	s_add_u32 s76, s76, 0x100
	s_addc_u32 s77, s77, 0
	s_cmp_gt_u32 s78, 29
	s_cbranch_scc0 .LBB0_709
	s_and_b64 vcc, exec, s[12:13]
	s_cbranch_vccz .LBB0_712
	s_barrier

.LBB0_847:
	s_ashr_i32 s23, s22, 31
	s_lshl_b64 s[24:25], s[22:23], 20
	s_add_u32 s24, s20, s24
	s_addc_u32 s25, s21, s25
	s_and_b64 s[26:27], s[2:3], exec
	s_cselect_b32 s23, s25, s31
	s_cselect_b32 s66, s24, s30
	s_ashr_i32 s19, s18, 31
	s_lshl_b64 s[26:27], s[18:19], 20
	v_readlane_b32 s68, v254, 24
	s_add_u32 s26, s68, s26
	s_addc_u32 s27, s74, s27
	s_and_b64 s[36:37], s[2:3], exec
	s_cselect_b32 s19, s27, s35
	s_cselect_b32 s67, s26, s34
	s_add_u32 s30, s30, 0x80080
	s_addc_u32 s31, s31, 0
	v_readlane_b32 s69, v254, 25
	v_readlane_b32 s70, v254, 26
	s_add_u32 s68, s34, 0x100
	v_mov_b32_e32 v2, 0
	s_addc_u32 s69, s35, 0
	s_mov_b32 s70, -2
	v_mov_b32_e32 v3, v2
	v_mov_b32_e32 v4, v2
	v_mov_b32_e32 v5, v2
	v_mov_b32_e32 v6, v2
	v_mov_b32_e32 v7, v2
	v_mov_b32_e32 v8, v2
	v_mov_b32_e32 v9, v2
	v_mov_b32_e32 v18, v2
	v_mov_b32_e32 v19, v2
	v_mov_b32_e32 v20, v2
	v_mov_b32_e32 v21, v2
	v_mov_b32_e32 v22, v2
	v_mov_b32_e32 v23, v2
	v_mov_b32_e32 v24, v2
	v_mov_b32_e32 v25, v2
	v_mov_b32_e32 v34, v2
	v_mov_b32_e32 v35, v2
	v_mov_b32_e32 v36, v2
	v_mov_b32_e32 v37, v2
	v_mov_b32_e32 v38, v2
	v_mov_b32_e32 v39, v2
	v_mov_b32_e32 v40, v2
	v_mov_b32_e32 v41, v2
	v_mov_b32_e32 v50, v2
	v_mov_b32_e32 v51, v2
	v_mov_b32_e32 v52, v2
	v_mov_b32_e32 v53, v2
	v_mov_b32_e32 v54, v2
	v_mov_b32_e32 v55, v2
	v_mov_b32_e32 v56, v2
	v_mov_b32_e32 v57, v2
	v_mov_b32_e32 v10, v2
	v_mov_b32_e32 v11, v2
	v_mov_b32_e32 v12, v2
	v_mov_b32_e32 v13, v2
	v_mov_b32_e32 v14, v2
	v_mov_b32_e32 v15, v2
	v_mov_b32_e32 v16, v2
	v_mov_b32_e32 v17, v2
	v_mov_b32_e32 v26, v2
	v_mov_b32_e32 v27, v2
	v_mov_b32_e32 v28, v2
	v_mov_b32_e32 v29, v2
	v_mov_b32_e32 v30, v2
	v_mov_b32_e32 v31, v2
	v_mov_b32_e32 v32, v2
	v_mov_b32_e32 v33, v2
	v_mov_b32_e32 v42, v2
	v_mov_b32_e32 v43, v2
	v_mov_b32_e32 v44, v2
	v_mov_b32_e32 v45, v2
	v_mov_b32_e32 v46, v2
	v_mov_b32_e32 v47, v2
	v_mov_b32_e32 v48, v2
	v_mov_b32_e32 v49, v2
	v_mov_b32_e32 v58, v2
	v_mov_b32_e32 v59, v2
	v_mov_b32_e32 v60, v2
	v_mov_b32_e32 v61, v2
	v_mov_b32_e32 v62, v2
	v_mov_b32_e32 v63, v2
	v_mov_b32_e32 v64, v2
	v_mov_b32_e32 v65, v2
	v_mov_b32_e32 v66, v2
	v_mov_b32_e32 v67, v2
	v_mov_b32_e32 v68, v2
	v_mov_b32_e32 v69, v2
	v_mov_b32_e32 v70, v2
	v_mov_b32_e32 v71, v2
	v_mov_b32_e32 v72, v2
	v_mov_b32_e32 v73, v2
	v_mov_b32_e32 v82, v2
	v_mov_b32_e32 v83, v2
	v_mov_b32_e32 v84, v2
	v_mov_b32_e32 v85, v2
	v_mov_b32_e32 v86, v2
	v_mov_b32_e32 v87, v2
	v_mov_b32_e32 v88, v2
	v_mov_b32_e32 v89, v2
	v_mov_b32_e32 v98, v2
	v_mov_b32_e32 v99, v2
	v_mov_b32_e32 v100, v2
	v_mov_b32_e32 v101, v2
	v_mov_b32_e32 v102, v2
	v_mov_b32_e32 v103, v2
	v_mov_b32_e32 v104, v2
	v_mov_b32_e32 v105, v2
	v_mov_b32_e32 v130, v2
	v_mov_b32_e32 v131, v2
	v_mov_b32_e32 v132, v2
	v_mov_b32_e32 v133, v2
	v_mov_b32_e32 v134, v2
	v_mov_b32_e32 v135, v2
	v_mov_b32_e32 v136, v2
	v_mov_b32_e32 v137, v2
	v_mov_b32_e32 v74, v2
	v_mov_b32_e32 v75, v2
	v_mov_b32_e32 v76, v2
	v_mov_b32_e32 v77, v2
	v_mov_b32_e32 v78, v2
	v_mov_b32_e32 v79, v2
	v_mov_b32_e32 v80, v2
	v_mov_b32_e32 v81, v2
	v_mov_b32_e32 v90, v2
	v_mov_b32_e32 v91, v2
	v_mov_b32_e32 v92, v2
	v_mov_b32_e32 v93, v2
	v_mov_b32_e32 v94, v2
	v_mov_b32_e32 v95, v2
	v_mov_b32_e32 v96, v2
	v_mov_b32_e32 v97, v2
	v_mov_b32_e32 v114, v2
	v_mov_b32_e32 v115, v2
	v_mov_b32_e32 v116, v2
	v_mov_b32_e32 v117, v2
	v_mov_b32_e32 v118, v2
	v_mov_b32_e32 v119, v2
	v_mov_b32_e32 v120, v2
	v_mov_b32_e32 v121, v2
	v_mov_b32_e32 v138, v2
	v_mov_b32_e32 v139, v2
	v_mov_b32_e32 v140, v2
	v_mov_b32_e32 v141, v2
	v_mov_b32_e32 v142, v2
	v_mov_b32_e32 v143, v2
	v_mov_b32_e32 v144, v2
	v_mov_b32_e32 v145, v2
	v_readlane_b32 s71, v254, 27
	v_add_u32_e32 v180, 0x18000, v171
	v_add_u32_e32 v181, 0x1c000, v171
.LBB0_848:
	ds_read_b128 v[106:109], v173
	ds_read_b128 v[110:113], v173 offset:1024
	ds_read_b128 v[122:125], v173 offset:2048
	ds_read_b128 v[126:129], v173 offset:3072
	ds_read_b128 v[176:179], v174
	ds_read_b128 v[184:187], v174 offset:1024
	ds_read_b128 v[188:191], v174 offset:2048
	ds_read_b128 v[192:195], v174 offset:3072
	s_add_u32 s34, s30, 0xfff80080
	s_addc_u32 s35, s31, -1
	s_cmp_eq_u32 s70, 28
	s_cselect_b32 s37, s23, s35
	s_cselect_b32 s36, s66, s34
	s_cselect_b32 s35, s19, s69
	s_cselect_b32 s34, s67, s68
	s_add_i32 m0, s29, 0xc000
	ds_read_b128 v[196:199], v175
	ds_read_b128 v[200:203], v175 offset:1024
	ds_read_b128 v[204:207], v175 offset:2048
	ds_read_b128 v[208:211], v175 offset:3072
	ds_read_b128 v[212:215], v175 offset:4096
	ds_read_b128 v[216:219], v175 offset:5120
	ds_read_b128 v[220:223], v175 offset:6144
	ds_read_b128 v[224:227], v175 offset:7168
	global_load_lds_dwordx4 v152, s[30:31]
	s_add_i32 m0, s29, 0xe000
	s_nop 0
	global_load_lds_dwordx4 v154, s[30:31]
	s_waitcnt vmcnt(8)
	s_waitcnt lgkmcnt(0)
	s_barrier
	s_setprio 1
	s_waitcnt lgkmcnt(0)
	v_mfma_i32_16x16x64_i8 v[142:145], v[106:109], v[196:199], v[142:145]
	v_mfma_i32_16x16x64_i8 v[138:141], v[122:125], v[196:199], v[138:141]
	v_mfma_i32_16x16x64_i8 v[118:121], v[106:109], v[204:207], v[118:121]
	v_mfma_i32_16x16x64_i8 v[114:117], v[122:125], v[204:207], v[114:117]
	v_mfma_i32_16x16x64_i8 v[94:97], v[106:109], v[212:215], v[94:97]
	v_mfma_i32_16x16x64_i8 v[90:93], v[122:125], v[212:215], v[90:93]
	v_mfma_i32_16x16x64_i8 v[78:81], v[106:109], v[220:223], v[78:81]
	v_mfma_i32_16x16x64_i8 v[74:77], v[122:125], v[220:223], v[74:77]
	v_mfma_i32_16x16x64_i8 v[142:145], v[110:113], v[200:203], v[142:145]
	v_mfma_i32_16x16x64_i8 v[138:141], v[126:129], v[200:203], v[138:141]
	v_mfma_i32_16x16x64_i8 v[118:121], v[110:113], v[208:211], v[118:121]
	v_mfma_i32_16x16x64_i8 v[114:117], v[126:129], v[208:211], v[114:117]
	v_mfma_i32_16x16x64_i8 v[94:97], v[110:113], v[216:219], v[94:97]
	v_mfma_i32_16x16x64_i8 v[90:93], v[126:129], v[216:219], v[90:93]
	v_mfma_i32_16x16x64_i8 v[78:81], v[110:113], v[224:227], v[78:81]
	v_mfma_i32_16x16x64_i8 v[74:77], v[126:129], v[224:227], v[74:77]
	s_setprio 0
	s_setprio 1
	v_mfma_i32_16x16x64_i8 v[134:137], v[176:179], v[196:199], v[134:137]
	v_mfma_i32_16x16x64_i8 v[130:133], v[188:191], v[196:199], v[130:133]
	v_mfma_i32_16x16x64_i8 v[102:105], v[176:179], v[204:207], v[102:105]
	v_mfma_i32_16x16x64_i8 v[98:101], v[188:191], v[204:207], v[98:101]
	v_mfma_i32_16x16x64_i8 v[86:89], v[176:179], v[212:215], v[86:89]
	v_mfma_i32_16x16x64_i8 v[82:85], v[188:191], v[212:215], v[82:85]
	v_mfma_i32_16x16x64_i8 v[70:73], v[176:179], v[220:223], v[70:73]
	v_mfma_i32_16x16x64_i8 v[66:69], v[188:191], v[220:223], v[66:69]
	v_mfma_i32_16x16x64_i8 v[134:137], v[184:187], v[200:203], v[134:137]
	v_mfma_i32_16x16x64_i8 v[130:133], v[192:195], v[200:203], v[130:133]
	v_mfma_i32_16x16x64_i8 v[102:105], v[184:187], v[208:211], v[102:105]
	v_mfma_i32_16x16x64_i8 v[98:101], v[192:195], v[208:211], v[98:101]
	v_mfma_i32_16x16x64_i8 v[86:89], v[184:187], v[216:219], v[86:89]
	v_mfma_i32_16x16x64_i8 v[82:85], v[192:195], v[216:219], v[82:85]
	v_mfma_i32_16x16x64_i8 v[70:73], v[184:187], v[224:227], v[70:73]
	v_mfma_i32_16x16x64_i8 v[66:69], v[192:195], v[224:227], v[66:69]
	s_setprio 0
	s_barrier
	s_add_i32 s71, s51, s39
	s_mov_b32 m0, s71
	ds_read_b128 v[196:199], v175 offset:16384
	ds_read_b128 v[200:203], v175 offset:17408
	ds_read_b128 v[204:207], v175 offset:18432
	ds_read_b128 v[208:211], v175 offset:19456
	ds_read_b128 v[212:215], v175 offset:20480
	ds_read_b128 v[216:219], v175 offset:21504
	ds_read_b128 v[220:223], v175 offset:22528
	ds_read_b128 v[224:227], v175 offset:23552
	global_load_lds_dwordx4 v146, s[34:35]
	s_add_i32 m0, s71, 0x2000
	s_add_u32 s72, s34, 0x80000
	s_addc_u32 s73, s35, 0
	s_add_i32 s71, s52, s39
	global_load_lds_dwordx4 v148, s[34:35]
	s_mov_b32 m0, s71
	s_nop 0
	global_load_lds_dwordx4 v146, s[72:73]
	s_add_i32 m0, s71, 0x2000
	s_nop 0
	global_load_lds_dwordx4 v148, s[72:73]
	s_mov_b32 m0, s29
	s_nop 0
	global_load_lds_dwordx4 v146, s[36:37]
	s_mov_b32 m0, s40
	s_nop 0
	global_load_lds_dwordx4 v148, s[36:37]
	s_waitcnt vmcnt(8)
	s_waitcnt lgkmcnt(0)
	s_barrier
	s_setprio 1
	s_waitcnt lgkmcnt(0)
	v_mfma_i32_16x16x64_i8 v[62:65], v[106:109], v[196:199], v[62:65]
	v_mfma_i32_16x16x64_i8 v[58:61], v[122:125], v[196:199], v[58:61]
	v_mfma_i32_16x16x64_i8 v[46:49], v[106:109], v[204:207], v[46:49]
	v_mfma_i32_16x16x64_i8 v[42:45], v[122:125], v[204:207], v[42:45]
	v_mfma_i32_16x16x64_i8 v[30:33], v[106:109], v[212:215], v[30:33]
	v_mfma_i32_16x16x64_i8 v[26:29], v[122:125], v[212:215], v[26:29]
	v_mfma_i32_16x16x64_i8 v[14:17], v[106:109], v[220:223], v[14:17]
	v_mfma_i32_16x16x64_i8 v[10:13], v[122:125], v[220:223], v[10:13]
	v_mfma_i32_16x16x64_i8 v[62:65], v[110:113], v[200:203], v[62:65]
	v_mfma_i32_16x16x64_i8 v[58:61], v[126:129], v[200:203], v[58:61]
	v_mfma_i32_16x16x64_i8 v[46:49], v[110:113], v[208:211], v[46:49]
	v_mfma_i32_16x16x64_i8 v[42:45], v[126:129], v[208:211], v[42:45]
	v_mfma_i32_16x16x64_i8 v[30:33], v[110:113], v[216:219], v[30:33]
	v_mfma_i32_16x16x64_i8 v[26:29], v[126:129], v[216:219], v[26:29]
	v_mfma_i32_16x16x64_i8 v[14:17], v[110:113], v[224:227], v[14:17]
	v_mfma_i32_16x16x64_i8 v[10:13], v[126:129], v[224:227], v[10:13]
	s_setprio 0
	s_setprio 1
	v_mfma_i32_16x16x64_i8 v[54:57], v[176:179], v[196:199], v[54:57]
	v_mfma_i32_16x16x64_i8 v[50:53], v[188:191], v[196:199], v[50:53]
	v_mfma_i32_16x16x64_i8 v[38:41], v[176:179], v[204:207], v[38:41]
	v_mfma_i32_16x16x64_i8 v[34:37], v[188:191], v[204:207], v[34:37]
	v_mfma_i32_16x16x64_i8 v[22:25], v[176:179], v[212:215], v[22:25]
	v_mfma_i32_16x16x64_i8 v[18:21], v[188:191], v[212:215], v[18:21]
	v_mfma_i32_16x16x64_i8 v[6:9], v[176:179], v[220:223], v[6:9]
	v_mfma_i32_16x16x64_i8 v[2:5], v[188:191], v[220:223], v[2:5]
	v_mfma_i32_16x16x64_i8 v[54:57], v[184:187], v[200:203], v[54:57]
	v_mfma_i32_16x16x64_i8 v[50:53], v[192:195], v[200:203], v[50:53]
	v_mfma_i32_16x16x64_i8 v[38:41], v[184:187], v[208:211], v[38:41]
	v_mfma_i32_16x16x64_i8 v[34:37], v[192:195], v[208:211], v[34:37]
	v_mfma_i32_16x16x64_i8 v[22:25], v[184:187], v[216:219], v[22:25]
	v_mfma_i32_16x16x64_i8 v[18:21], v[192:195], v[216:219], v[18:21]
	v_mfma_i32_16x16x64_i8 v[6:9], v[184:187], v[224:227], v[6:9]
	v_mfma_i32_16x16x64_i8 v[2:5], v[192:195], v[224:227], v[2:5]
	s_setprio 0
	s_barrier
	s_add_i32 s71, 0, 0x18000
	s_add_i32 s72, 0, 0x1c000
	ds_read_b128 v[106:109], v180
	ds_read_b128 v[110:113], v180 offset:1024
	ds_read_b128 v[122:125], v180 offset:2048
	ds_read_b128 v[126:129], v180 offset:3072
	ds_read_b128 v[176:179], v181
	ds_read_b128 v[184:187], v181 offset:1024
	ds_read_b128 v[188:191], v181 offset:2048
	ds_read_b128 v[192:195], v181 offset:3072
	s_add_u32 s36, s36, 0x80000
	s_addc_u32 s37, s37, 0
	s_mov_b32 m0, s41
	ds_read_b128 v[196:199], v175 offset:32768
	ds_read_b128 v[200:203], v175 offset:33792
	ds_read_b128 v[204:207], v175 offset:34816
	ds_read_b128 v[208:211], v175 offset:35840
	ds_read_b128 v[212:215], v175 offset:36864
	ds_read_b128 v[216:219], v175 offset:37888
	ds_read_b128 v[220:223], v175 offset:38912
	ds_read_b128 v[224:227], v175 offset:39936
	global_load_lds_dwordx4 v146, s[36:37]
	s_mov_b32 m0, s42
	s_nop 0
	global_load_lds_dwordx4 v148, s[36:37]
	s_waitcnt vmcnt(8)
	s_waitcnt lgkmcnt(0)
	s_barrier
	s_setprio 1
	s_waitcnt lgkmcnt(0)
	v_mfma_i32_16x16x64_i8 v[142:145], v[106:109], v[196:199], v[142:145]
	v_mfma_i32_16x16x64_i8 v[138:141], v[122:125], v[196:199], v[138:141]
	v_mfma_i32_16x16x64_i8 v[118:121], v[106:109], v[204:207], v[118:121]
	v_mfma_i32_16x16x64_i8 v[114:117], v[122:125], v[204:207], v[114:117]
	v_mfma_i32_16x16x64_i8 v[94:97], v[106:109], v[212:215], v[94:97]
	v_mfma_i32_16x16x64_i8 v[90:93], v[122:125], v[212:215], v[90:93]
	v_mfma_i32_16x16x64_i8 v[78:81], v[106:109], v[220:223], v[78:81]
	v_mfma_i32_16x16x64_i8 v[74:77], v[122:125], v[220:223], v[74:77]
	v_mfma_i32_16x16x64_i8 v[142:145], v[110:113], v[200:203], v[142:145]
	v_mfma_i32_16x16x64_i8 v[138:141], v[126:129], v[200:203], v[138:141]
	v_mfma_i32_16x16x64_i8 v[118:121], v[110:113], v[208:211], v[118:121]
	v_mfma_i32_16x16x64_i8 v[114:117], v[126:129], v[208:211], v[114:117]
	v_mfma_i32_16x16x64_i8 v[94:97], v[110:113], v[216:219], v[94:97]
	v_mfma_i32_16x16x64_i8 v[90:93], v[126:129], v[216:219], v[90:93]
	v_mfma_i32_16x16x64_i8 v[78:81], v[110:113], v[224:227], v[78:81]
	v_mfma_i32_16x16x64_i8 v[74:77], v[126:129], v[224:227], v[74:77]
	s_setprio 0
	s_setprio 1
	v_mfma_i32_16x16x64_i8 v[134:137], v[176:179], v[196:199], v[134:137]
	v_mfma_i32_16x16x64_i8 v[130:133], v[188:191], v[196:199], v[130:133]
	v_mfma_i32_16x16x64_i8 v[102:105], v[176:179], v[204:207], v[102:105]
	v_mfma_i32_16x16x64_i8 v[98:101], v[188:191], v[204:207], v[98:101]
	v_mfma_i32_16x16x64_i8 v[86:89], v[176:179], v[212:215], v[86:89]
	v_mfma_i32_16x16x64_i8 v[82:85], v[188:191], v[212:215], v[82:85]
	v_mfma_i32_16x16x64_i8 v[70:73], v[176:179], v[220:223], v[70:73]
	v_mfma_i32_16x16x64_i8 v[66:69], v[188:191], v[220:223], v[66:69]
	v_mfma_i32_16x16x64_i8 v[134:137], v[184:187], v[200:203], v[134:137]
	v_mfma_i32_16x16x64_i8 v[130:133], v[192:195], v[200:203], v[130:133]
	v_mfma_i32_16x16x64_i8 v[102:105], v[184:187], v[208:211], v[102:105]
	v_mfma_i32_16x16x64_i8 v[98:101], v[192:195], v[208:211], v[98:101]
	v_mfma_i32_16x16x64_i8 v[86:89], v[184:187], v[216:219], v[86:89]
	v_mfma_i32_16x16x64_i8 v[82:85], v[192:195], v[216:219], v[82:85]
	v_mfma_i32_16x16x64_i8 v[70:73], v[184:187], v[224:227], v[70:73]
	v_mfma_i32_16x16x64_i8 v[66:69], v[192:195], v[224:227], v[66:69]
	s_setprio 0
	s_barrier
	s_add_u32 s98, s36, 0xfff80080
	s_addc_u32 s99, s37, -1
	s_add_i32 s36, s71, s39
	s_mov_b32 m0, s36
	ds_read_b128 v[196:199], v175 offset:49152
	ds_read_b128 v[200:203], v175 offset:50176
	ds_read_b128 v[204:207], v175 offset:51200
	ds_read_b128 v[208:211], v175 offset:52224
	ds_read_b128 v[212:215], v175 offset:53248
	ds_read_b128 v[216:219], v175 offset:54272
	ds_read_b128 v[220:223], v175 offset:55296
	ds_read_b128 v[224:227], v175 offset:56320
	s_add_u32 s100, s34, 0x80
	s_addc_u32 s101, s35, 0
	global_load_lds_dwordx4 v146, s[100:101]
	s_add_i32 m0, s36, 0x2000
	s_add_u32 s34, s34, 0x80080
	s_addc_u32 s35, s35, 0
	s_add_i32 s36, s72, s39
	global_load_lds_dwordx4 v148, s[100:101]
	s_mov_b32 m0, s36
	s_nop 0
	global_load_lds_dwordx4 v146, s[34:35]
	s_add_i32 m0, s36, 0x2000
	s_nop 0
	global_load_lds_dwordx4 v148, s[34:35]
	s_mov_b32 m0, s46
	s_nop 0
	global_load_lds_dwordx4 v146, s[98:99]
	s_mov_b32 m0, s47
	s_nop 0
	global_load_lds_dwordx4 v148, s[98:99]
	s_waitcnt vmcnt(8)
	s_waitcnt lgkmcnt(0)
	s_barrier
	s_setprio 1
	s_waitcnt lgkmcnt(0)
	v_mfma_i32_16x16x64_i8 v[62:65], v[106:109], v[196:199], v[62:65]
	v_mfma_i32_16x16x64_i8 v[58:61], v[122:125], v[196:199], v[58:61]
	v_mfma_i32_16x16x64_i8 v[46:49], v[106:109], v[204:207], v[46:49]
	v_mfma_i32_16x16x64_i8 v[42:45], v[122:125], v[204:207], v[42:45]
	v_mfma_i32_16x16x64_i8 v[30:33], v[106:109], v[212:215], v[30:33]
	v_mfma_i32_16x16x64_i8 v[26:29], v[122:125], v[212:215], v[26:29]
	v_mfma_i32_16x16x64_i8 v[14:17], v[106:109], v[220:223], v[14:17]
	v_mfma_i32_16x16x64_i8 v[10:13], v[122:125], v[220:223], v[10:13]
	v_mfma_i32_16x16x64_i8 v[62:65], v[110:113], v[200:203], v[62:65]
	v_mfma_i32_16x16x64_i8 v[58:61], v[126:129], v[200:203], v[58:61]
	v_mfma_i32_16x16x64_i8 v[46:49], v[110:113], v[208:211], v[46:49]
	v_mfma_i32_16x16x64_i8 v[42:45], v[126:129], v[208:211], v[42:45]
	v_mfma_i32_16x16x64_i8 v[30:33], v[110:113], v[216:219], v[30:33]
	v_mfma_i32_16x16x64_i8 v[26:29], v[126:129], v[216:219], v[26:29]
	v_mfma_i32_16x16x64_i8 v[14:17], v[110:113], v[224:227], v[14:17]
	v_mfma_i32_16x16x64_i8 v[10:13], v[126:129], v[224:227], v[10:13]
	s_setprio 0
	s_setprio 1
	v_mfma_i32_16x16x64_i8 v[54:57], v[176:179], v[196:199], v[54:57]
	v_mfma_i32_16x16x64_i8 v[50:53], v[188:191], v[196:199], v[50:53]
	v_mfma_i32_16x16x64_i8 v[38:41], v[176:179], v[204:207], v[38:41]
	v_mfma_i32_16x16x64_i8 v[34:37], v[188:191], v[204:207], v[34:37]
	v_mfma_i32_16x16x64_i8 v[22:25], v[176:179], v[212:215], v[22:25]
	v_mfma_i32_16x16x64_i8 v[18:21], v[188:191], v[212:215], v[18:21]
	v_mfma_i32_16x16x64_i8 v[6:9], v[176:179], v[220:223], v[6:9]
	v_mfma_i32_16x16x64_i8 v[2:5], v[188:191], v[220:223], v[2:5]
	v_mfma_i32_16x16x64_i8 v[54:57], v[184:187], v[200:203], v[54:57]
	v_mfma_i32_16x16x64_i8 v[50:53], v[192:195], v[200:203], v[50:53]
	v_mfma_i32_16x16x64_i8 v[38:41], v[184:187], v[208:211], v[38:41]
	v_mfma_i32_16x16x64_i8 v[34:37], v[192:195], v[208:211], v[34:37]
	v_mfma_i32_16x16x64_i8 v[22:25], v[184:187], v[216:219], v[22:25]
	v_mfma_i32_16x16x64_i8 v[18:21], v[192:195], v[216:219], v[18:21]
	v_mfma_i32_16x16x64_i8 v[6:9], v[184:187], v[224:227], v[6:9]
	v_mfma_i32_16x16x64_i8 v[2:5], v[192:195], v[224:227], v[2:5]
	s_setprio 0
	s_barrier
	s_add_i32 s70, s70, 2
	s_add_u32 s30, s30, 0x100
	s_addc_u32 s31, s31, 0
	s_add_u32 s68, s68, 0x100
	s_addc_u32 s69, s69, 0
	s_cmp_gt_u32 s70, 29
	s_cbranch_scc0 .LBB0_848
	s_and_b64 vcc, exec, s[8:9]
	s_cbranch_vccz .LBB0_851
	s_barrier

.LBB0_936:
	s_ashr_i32 s21, s20, 31
	s_lshl_b64 s[22:23], s[20:21], 23
	s_add_u32 s22, s48, s22
	s_addc_u32 s23, s49, s23
	s_and_b64 s[24:25], s[2:3], exec
	s_cselect_b32 s21, s23, s29
	s_cselect_b32 s66, s22, s28
	s_ashr_i32 s19, s18, 31
	s_lshl_b64 s[24:25], s[18:19], 23
	s_add_u32 s24, s44, s24
	s_addc_u32 s25, s45, s25
	s_and_b64 s[34:35], s[2:3], exec
	s_cselect_b32 s19, s25, s31
	s_cselect_b32 s67, s24, s30
	s_add_u32 s28, s28, 0x400080
	s_addc_u32 s29, s29, 0
	s_add_u32 s68, s30, 0x100
	v_mov_b32_e32 v0, 0
	s_addc_u32 s69, s31, 0
	s_mov_b32 s70, -2
	v_mov_b32_e32 v1, v0
	v_mov_b32_e32 v2, v0
	v_mov_b32_e32 v3, v0
	v_mov_b32_e32 v4, v0
	v_mov_b32_e32 v5, v0
	v_mov_b32_e32 v6, v0
	v_mov_b32_e32 v7, v0
	v_mov_b32_e32 v8, v0
	v_mov_b32_e32 v9, v0
	v_mov_b32_e32 v10, v0
	v_mov_b32_e32 v11, v0
	v_mov_b32_e32 v16, v0
	v_mov_b32_e32 v17, v0
	v_mov_b32_e32 v18, v0
	v_mov_b32_e32 v19, v0
	v_mov_b32_e32 v24, v0
	v_mov_b32_e32 v25, v0
	v_mov_b32_e32 v26, v0
	v_mov_b32_e32 v27, v0
	v_mov_b32_e32 v32, v0
	v_mov_b32_e32 v33, v0
	v_mov_b32_e32 v34, v0
	v_mov_b32_e32 v35, v0
	v_mov_b32_e32 v40, v0
	v_mov_b32_e32 v41, v0
	v_mov_b32_e32 v42, v0
	v_mov_b32_e32 v43, v0
	s_waitcnt vmcnt(0)
	v_mov_b32_e32 v48, v0
	v_mov_b32_e32 v49, v0
	v_mov_b32_e32 v50, v0
	v_mov_b32_e32 v51, v0
	v_mov_b32_e32 v12, v0
	v_mov_b32_e32 v13, v0
	v_mov_b32_e32 v14, v0
	v_mov_b32_e32 v15, v0
	v_mov_b32_e32 v20, v0
	v_mov_b32_e32 v21, v0
	v_mov_b32_e32 v22, v0
	v_mov_b32_e32 v23, v0
	v_mov_b32_e32 v28, v0
	v_mov_b32_e32 v29, v0
	v_mov_b32_e32 v30, v0
	v_mov_b32_e32 v31, v0
	v_mov_b32_e32 v36, v0
	v_mov_b32_e32 v37, v0
	v_mov_b32_e32 v38, v0
	v_mov_b32_e32 v39, v0
	v_mov_b32_e32 v44, v0
	v_mov_b32_e32 v45, v0
	v_mov_b32_e32 v46, v0
	v_mov_b32_e32 v47, v0
	v_mov_b32_e32 v52, v0
	v_mov_b32_e32 v53, v0
	v_mov_b32_e32 v54, v0
	v_mov_b32_e32 v55, v0
	v_mov_b32_e32 v56, v0
	v_mov_b32_e32 v57, v0
	v_mov_b32_e32 v58, v0
	v_mov_b32_e32 v59, v0
	v_mov_b32_e32 v60, v0
	v_mov_b32_e32 v61, v0
	v_mov_b32_e32 v62, v0
	v_mov_b32_e32 v63, v0
	v_mov_b32_e32 v64, v0
	v_mov_b32_e32 v65, v0
	v_mov_b32_e32 v66, v0
	v_mov_b32_e32 v67, v0
	v_mov_b32_e32 v68, v0
	v_mov_b32_e32 v69, v0
	v_mov_b32_e32 v70, v0
	v_mov_b32_e32 v71, v0
	v_mov_b32_e32 v80, v0
	v_mov_b32_e32 v81, v0
	v_mov_b32_e32 v82, v0
	v_mov_b32_e32 v83, v0
	v_mov_b32_e32 v84, v0
	v_mov_b32_e32 v85, v0
	v_mov_b32_e32 v86, v0
	v_mov_b32_e32 v87, v0
	v_mov_b32_e32 v88, v0
	v_mov_b32_e32 v89, v0
	v_mov_b32_e32 v90, v0
	v_mov_b32_e32 v91, v0
	v_mov_b32_e32 v92, v0
	v_mov_b32_e32 v93, v0
	v_mov_b32_e32 v94, v0
	v_mov_b32_e32 v95, v0
	v_mov_b32_e32 v96, v0
	v_mov_b32_e32 v97, v0
	v_mov_b32_e32 v98, v0
	v_mov_b32_e32 v99, v0
	v_mov_b32_e32 v104, v0
	v_mov_b32_e32 v105, v0
	v_mov_b32_e32 v106, v0
	v_mov_b32_e32 v107, v0
	v_mov_b32_e32 v72, v0
	v_mov_b32_e32 v73, v0
	v_mov_b32_e32 v74, v0
	v_mov_b32_e32 v75, v0
	v_mov_b32_e32 v76, v0
	v_mov_b32_e32 v77, v0
	v_mov_b32_e32 v78, v0
	v_mov_b32_e32 v79, v0
	v_mov_b32_e32 v100, v0
	v_mov_b32_e32 v101, v0
	v_mov_b32_e32 v102, v0
	v_mov_b32_e32 v103, v0
	v_mov_b32_e32 v108, v0
	v_mov_b32_e32 v109, v0
	v_mov_b32_e32 v110, v0
	v_mov_b32_e32 v111, v0
	v_mov_b32_e32 v112, v0
	v_mov_b32_e32 v113, v0
	v_mov_b32_e32 v114, v0
	v_mov_b32_e32 v115, v0
	v_mov_b32_e32 v116, v0
	v_mov_b32_e32 v117, v0
	v_mov_b32_e32 v118, v0
	v_mov_b32_e32 v119, v0
	v_mov_b32_e32 v120, v0
	v_mov_b32_e32 v121, v0
	v_mov_b32_e32 v122, v0
	v_mov_b32_e32 v123, v0
	v_mov_b32_e32 v124, v0
	v_mov_b32_e32 v125, v0
	v_mov_b32_e32 v126, v0
	v_mov_b32_e32 v127, v0
	v_add_u32_e32 v212, 0x18000, v157
	v_add_u32_e32 v213, 0x1c000, v157
.LBB0_937:
	ds_read_b128 v[128:131], v159
	ds_read_b128 v[132:135], v159 offset:1024
	ds_read_b128 v[136:139], v159 offset:2048
	ds_read_b128 v[140:143], v159 offset:3072
	ds_read_b128 v[162:165], v160
	ds_read_b128 v[166:169], v160 offset:1024
	ds_read_b128 v[170:173], v160 offset:2048
	ds_read_b128 v[174:177], v160 offset:3072
	s_add_u32 s30, s28, 0xffc00080
	s_addc_u32 s31, s29, -1
	s_cmpk_eq_i32 s70, 0xfc
	s_cselect_b32 s35, s21, s31
	s_cselect_b32 s34, s66, s30
	s_cselect_b32 s31, s19, s69
	s_cselect_b32 s30, s67, s68
	s_add_i32 m0, s27, 0xc000
	ds_read_b128 v[178:181], v161
	ds_read_b128 v[184:187], v161 offset:1024
	ds_read_b128 v[188:191], v161 offset:2048
	ds_read_b128 v[192:195], v161 offset:3072
	ds_read_b128 v[196:199], v161 offset:4096
	ds_read_b128 v[200:203], v161 offset:5120
	ds_read_b128 v[204:207], v161 offset:6144
	ds_read_b128 v[208:211], v161 offset:7168
	global_load_lds_dwordx4 v148, s[28:29]
	s_add_i32 m0, s27, 0xe000
	s_nop 0
	global_load_lds_dwordx4 v150, s[28:29]
	s_waitcnt vmcnt(8)
	s_waitcnt lgkmcnt(0)
	s_barrier
	s_setprio 1
	s_waitcnt lgkmcnt(0)
	v_mfma_f32_16x16x32_bf16 v[124:127], v[128:131], v[178:181], v[124:127]
	v_mfma_f32_16x16x32_bf16 v[120:123], v[136:139], v[178:181], v[120:123]
	v_mfma_f32_16x16x32_bf16 v[116:119], v[128:131], v[188:191], v[116:119]
	v_mfma_f32_16x16x32_bf16 v[112:115], v[136:139], v[188:191], v[112:115]
	v_mfma_f32_16x16x32_bf16 v[108:111], v[128:131], v[196:199], v[108:111]
	v_mfma_f32_16x16x32_bf16 v[100:103], v[136:139], v[196:199], v[100:103]
	v_mfma_f32_16x16x32_bf16 v[76:79], v[128:131], v[204:207], v[76:79]
	v_mfma_f32_16x16x32_bf16 v[72:75], v[136:139], v[204:207], v[72:75]
	v_mfma_f32_16x16x32_bf16 v[124:127], v[132:135], v[184:187], v[124:127]
	v_mfma_f32_16x16x32_bf16 v[120:123], v[140:143], v[184:187], v[120:123]
	v_mfma_f32_16x16x32_bf16 v[116:119], v[132:135], v[192:195], v[116:119]
	v_mfma_f32_16x16x32_bf16 v[112:115], v[140:143], v[192:195], v[112:115]
	v_mfma_f32_16x16x32_bf16 v[108:111], v[132:135], v[200:203], v[108:111]
	v_mfma_f32_16x16x32_bf16 v[100:103], v[140:143], v[200:203], v[100:103]
	v_mfma_f32_16x16x32_bf16 v[76:79], v[132:135], v[208:211], v[76:79]
	v_mfma_f32_16x16x32_bf16 v[72:75], v[140:143], v[208:211], v[72:75]
	s_setprio 0
	s_setprio 1
	v_mfma_f32_16x16x32_bf16 v[104:107], v[162:165], v[178:181], v[104:107]
	v_mfma_f32_16x16x32_bf16 v[96:99], v[170:173], v[178:181], v[96:99]
	v_mfma_f32_16x16x32_bf16 v[92:95], v[162:165], v[188:191], v[92:95]
	v_mfma_f32_16x16x32_bf16 v[88:91], v[170:173], v[188:191], v[88:91]
	v_mfma_f32_16x16x32_bf16 v[84:87], v[162:165], v[196:199], v[84:87]
	v_mfma_f32_16x16x32_bf16 v[80:83], v[170:173], v[196:199], v[80:83]
	v_mfma_f32_16x16x32_bf16 v[68:71], v[162:165], v[204:207], v[68:71]
	v_mfma_f32_16x16x32_bf16 v[64:67], v[170:173], v[204:207], v[64:67]
	v_mfma_f32_16x16x32_bf16 v[104:107], v[166:169], v[184:187], v[104:107]
	v_mfma_f32_16x16x32_bf16 v[96:99], v[174:177], v[184:187], v[96:99]
	v_mfma_f32_16x16x32_bf16 v[92:95], v[166:169], v[192:195], v[92:95]
	v_mfma_f32_16x16x32_bf16 v[88:91], v[174:177], v[192:195], v[88:91]
	v_mfma_f32_16x16x32_bf16 v[84:87], v[166:169], v[200:203], v[84:87]
	v_mfma_f32_16x16x32_bf16 v[80:83], v[174:177], v[200:203], v[80:83]
	v_mfma_f32_16x16x32_bf16 v[68:71], v[166:169], v[208:211], v[68:71]
	v_mfma_f32_16x16x32_bf16 v[64:67], v[174:177], v[208:211], v[64:67]
	s_setprio 0
	s_barrier
	s_add_i32 s71, s51, s36
	s_mov_b32 m0, s71
	ds_read_b128 v[178:181], v161 offset:16384
	ds_read_b128 v[184:187], v161 offset:17408
	ds_read_b128 v[188:191], v161 offset:18432
	ds_read_b128 v[192:195], v161 offset:19456
	ds_read_b128 v[196:199], v161 offset:20480
	ds_read_b128 v[200:203], v161 offset:21504
	ds_read_b128 v[204:207], v161 offset:22528
	ds_read_b128 v[208:211], v161 offset:23552
	global_load_lds_dwordx4 v144, s[30:31]
	s_add_i32 m0, s71, 0x2000
	s_add_u32 s72, s30, 0x400000
	s_addc_u32 s73, s31, 0
	s_add_i32 s71, s52, s36
	global_load_lds_dwordx4 v146, s[30:31]
	s_mov_b32 m0, s71
	s_nop 0
	global_load_lds_dwordx4 v144, s[72:73]
	s_add_i32 m0, s71, 0x2000
	s_nop 0
	global_load_lds_dwordx4 v146, s[72:73]
	s_mov_b32 m0, s27
	s_nop 0
	global_load_lds_dwordx4 v144, s[34:35]
	s_mov_b32 m0, s38
	s_nop 0
	global_load_lds_dwordx4 v146, s[34:35]
	s_waitcnt vmcnt(8)
	s_waitcnt lgkmcnt(0)
	s_barrier
	s_setprio 1
	s_waitcnt lgkmcnt(0)
	v_mfma_f32_16x16x32_bf16 v[60:63], v[128:131], v[178:181], v[60:63]
	v_mfma_f32_16x16x32_bf16 v[56:59], v[136:139], v[178:181], v[56:59]
	v_mfma_f32_16x16x32_bf16 v[52:55], v[128:131], v[188:191], v[52:55]
	v_mfma_f32_16x16x32_bf16 v[44:47], v[136:139], v[188:191], v[44:47]
	v_mfma_f32_16x16x32_bf16 v[36:39], v[128:131], v[196:199], v[36:39]
	v_mfma_f32_16x16x32_bf16 v[28:31], v[136:139], v[196:199], v[28:31]
	v_mfma_f32_16x16x32_bf16 v[20:23], v[128:131], v[204:207], v[20:23]
	v_mfma_f32_16x16x32_bf16 v[12:15], v[136:139], v[204:207], v[12:15]
	v_mfma_f32_16x16x32_bf16 v[60:63], v[132:135], v[184:187], v[60:63]
	v_mfma_f32_16x16x32_bf16 v[56:59], v[140:143], v[184:187], v[56:59]
	v_mfma_f32_16x16x32_bf16 v[52:55], v[132:135], v[192:195], v[52:55]
	v_mfma_f32_16x16x32_bf16 v[44:47], v[140:143], v[192:195], v[44:47]
	v_mfma_f32_16x16x32_bf16 v[36:39], v[132:135], v[200:203], v[36:39]
	v_mfma_f32_16x16x32_bf16 v[28:31], v[140:143], v[200:203], v[28:31]
	v_mfma_f32_16x16x32_bf16 v[20:23], v[132:135], v[208:211], v[20:23]
	v_mfma_f32_16x16x32_bf16 v[12:15], v[140:143], v[208:211], v[12:15]
	s_setprio 0
	s_setprio 1
	v_mfma_f32_16x16x32_bf16 v[48:51], v[162:165], v[178:181], v[48:51]
	v_mfma_f32_16x16x32_bf16 v[40:43], v[170:173], v[178:181], v[40:43]
	v_mfma_f32_16x16x32_bf16 v[32:35], v[162:165], v[188:191], v[32:35]
	v_mfma_f32_16x16x32_bf16 v[24:27], v[170:173], v[188:191], v[24:27]
	v_mfma_f32_16x16x32_bf16 v[16:19], v[162:165], v[196:199], v[16:19]
	v_mfma_f32_16x16x32_bf16 v[8:11], v[170:173], v[196:199], v[8:11]
	v_mfma_f32_16x16x32_bf16 v[4:7], v[162:165], v[204:207], v[4:7]
	v_mfma_f32_16x16x32_bf16 v[0:3], v[170:173], v[204:207], v[0:3]
	v_mfma_f32_16x16x32_bf16 v[48:51], v[166:169], v[184:187], v[48:51]
	v_mfma_f32_16x16x32_bf16 v[40:43], v[174:177], v[184:187], v[40:43]
	v_mfma_f32_16x16x32_bf16 v[32:35], v[166:169], v[192:195], v[32:35]
	v_mfma_f32_16x16x32_bf16 v[24:27], v[174:177], v[192:195], v[24:27]
	v_mfma_f32_16x16x32_bf16 v[16:19], v[166:169], v[200:203], v[16:19]
	v_mfma_f32_16x16x32_bf16 v[8:11], v[174:177], v[200:203], v[8:11]
	v_mfma_f32_16x16x32_bf16 v[4:7], v[166:169], v[208:211], v[4:7]
	v_mfma_f32_16x16x32_bf16 v[0:3], v[174:177], v[208:211], v[0:3]
	s_setprio 0
	s_barrier
	s_add_i32 s71, 0, 0x18000
	s_add_i32 s72, 0, 0x1c000
	ds_read_b128 v[128:131], v212
	ds_read_b128 v[132:135], v212 offset:1024
	ds_read_b128 v[136:139], v212 offset:2048
	ds_read_b128 v[140:143], v212 offset:3072
	ds_read_b128 v[162:165], v213
	ds_read_b128 v[166:169], v213 offset:1024
	ds_read_b128 v[170:173], v213 offset:2048
	ds_read_b128 v[174:177], v213 offset:3072
	s_add_u32 s34, s34, 0x400000
	s_addc_u32 s35, s35, 0
	s_mov_b32 m0, s39
	ds_read_b128 v[178:181], v161 offset:32768
	ds_read_b128 v[184:187], v161 offset:33792
	ds_read_b128 v[188:191], v161 offset:34816
	ds_read_b128 v[192:195], v161 offset:35840
	ds_read_b128 v[196:199], v161 offset:36864
	ds_read_b128 v[200:203], v161 offset:37888
	ds_read_b128 v[204:207], v161 offset:38912
	ds_read_b128 v[208:211], v161 offset:39936
	global_load_lds_dwordx4 v144, s[34:35]
	s_mov_b32 m0, s40
	s_nop 0
	global_load_lds_dwordx4 v146, s[34:35]
	s_waitcnt vmcnt(8)
	s_waitcnt lgkmcnt(0)
	s_barrier
	s_setprio 1
	s_waitcnt lgkmcnt(0)
	v_mfma_f32_16x16x32_bf16 v[124:127], v[128:131], v[178:181], v[124:127]
	v_mfma_f32_16x16x32_bf16 v[120:123], v[136:139], v[178:181], v[120:123]
	v_mfma_f32_16x16x32_bf16 v[116:119], v[128:131], v[188:191], v[116:119]
	v_mfma_f32_16x16x32_bf16 v[112:115], v[136:139], v[188:191], v[112:115]
	v_mfma_f32_16x16x32_bf16 v[108:111], v[128:131], v[196:199], v[108:111]
	v_mfma_f32_16x16x32_bf16 v[100:103], v[136:139], v[196:199], v[100:103]
	v_mfma_f32_16x16x32_bf16 v[76:79], v[128:131], v[204:207], v[76:79]
	v_mfma_f32_16x16x32_bf16 v[72:75], v[136:139], v[204:207], v[72:75]
	v_mfma_f32_16x16x32_bf16 v[124:127], v[132:135], v[184:187], v[124:127]
	v_mfma_f32_16x16x32_bf16 v[120:123], v[140:143], v[184:187], v[120:123]
	v_mfma_f32_16x16x32_bf16 v[116:119], v[132:135], v[192:195], v[116:119]
	v_mfma_f32_16x16x32_bf16 v[112:115], v[140:143], v[192:195], v[112:115]
	v_mfma_f32_16x16x32_bf16 v[108:111], v[132:135], v[200:203], v[108:111]
	v_mfma_f32_16x16x32_bf16 v[100:103], v[140:143], v[200:203], v[100:103]
	v_mfma_f32_16x16x32_bf16 v[76:79], v[132:135], v[208:211], v[76:79]
	v_mfma_f32_16x16x32_bf16 v[72:75], v[140:143], v[208:211], v[72:75]
	s_setprio 0
	s_setprio 1
	v_mfma_f32_16x16x32_bf16 v[104:107], v[162:165], v[178:181], v[104:107]
	v_mfma_f32_16x16x32_bf16 v[96:99], v[170:173], v[178:181], v[96:99]
	v_mfma_f32_16x16x32_bf16 v[92:95], v[162:165], v[188:191], v[92:95]
	v_mfma_f32_16x16x32_bf16 v[88:91], v[170:173], v[188:191], v[88:91]
	v_mfma_f32_16x16x32_bf16 v[84:87], v[162:165], v[196:199], v[84:87]
	v_mfma_f32_16x16x32_bf16 v[80:83], v[170:173], v[196:199], v[80:83]
	v_mfma_f32_16x16x32_bf16 v[68:71], v[162:165], v[204:207], v[68:71]
	v_mfma_f32_16x16x32_bf16 v[64:67], v[170:173], v[204:207], v[64:67]
	v_mfma_f32_16x16x32_bf16 v[104:107], v[166:169], v[184:187], v[104:107]
	v_mfma_f32_16x16x32_bf16 v[96:99], v[174:177], v[184:187], v[96:99]
	v_mfma_f32_16x16x32_bf16 v[92:95], v[166:169], v[192:195], v[92:95]
	v_mfma_f32_16x16x32_bf16 v[88:91], v[174:177], v[192:195], v[88:91]
	v_mfma_f32_16x16x32_bf16 v[84:87], v[166:169], v[200:203], v[84:87]
	v_mfma_f32_16x16x32_bf16 v[80:83], v[174:177], v[200:203], v[80:83]
	v_mfma_f32_16x16x32_bf16 v[68:71], v[166:169], v[208:211], v[68:71]
	v_mfma_f32_16x16x32_bf16 v[64:67], v[174:177], v[208:211], v[64:67]
	s_setprio 0
	s_barrier
	s_add_u32 s98, s34, 0xffc00080
	s_addc_u32 s99, s35, -1
	s_add_i32 s34, s71, s36
	s_mov_b32 m0, s34
	ds_read_b128 v[178:181], v161 offset:49152
	ds_read_b128 v[184:187], v161 offset:50176
	ds_read_b128 v[188:191], v161 offset:51200
	ds_read_b128 v[192:195], v161 offset:52224
	ds_read_b128 v[196:199], v161 offset:53248
	ds_read_b128 v[200:203], v161 offset:54272
	ds_read_b128 v[204:207], v161 offset:55296
	ds_read_b128 v[208:211], v161 offset:56320
	s_add_u32 s100, s30, 0x80
	s_addc_u32 s101, s31, 0
	global_load_lds_dwordx4 v144, s[100:101]
	s_add_i32 m0, s34, 0x2000
	s_add_u32 s30, s30, 0x400080
	s_addc_u32 s31, s31, 0
	s_add_i32 s34, s72, s36
	global_load_lds_dwordx4 v146, s[100:101]
	s_mov_b32 m0, s34
	s_nop 0
	global_load_lds_dwordx4 v144, s[30:31]
	s_add_i32 m0, s34, 0x2000
	s_nop 0
	global_load_lds_dwordx4 v146, s[30:31]
	s_mov_b32 m0, s47
	s_nop 0
	global_load_lds_dwordx4 v144, s[98:99]
	s_mov_b32 m0, s50
	s_nop 0
	global_load_lds_dwordx4 v146, s[98:99]
	s_waitcnt vmcnt(8)
	s_waitcnt lgkmcnt(0)
	s_barrier
	s_setprio 1
	s_waitcnt lgkmcnt(0)
	v_mfma_f32_16x16x32_bf16 v[60:63], v[128:131], v[178:181], v[60:63]
	v_mfma_f32_16x16x32_bf16 v[56:59], v[136:139], v[178:181], v[56:59]
	v_mfma_f32_16x16x32_bf16 v[52:55], v[128:131], v[188:191], v[52:55]
	v_mfma_f32_16x16x32_bf16 v[44:47], v[136:139], v[188:191], v[44:47]
	v_mfma_f32_16x16x32_bf16 v[36:39], v[128:131], v[196:199], v[36:39]
	v_mfma_f32_16x16x32_bf16 v[28:31], v[136:139], v[196:199], v[28:31]
	v_mfma_f32_16x16x32_bf16 v[20:23], v[128:131], v[204:207], v[20:23]
	v_mfma_f32_16x16x32_bf16 v[12:15], v[136:139], v[204:207], v[12:15]
	v_mfma_f32_16x16x32_bf16 v[60:63], v[132:135], v[184:187], v[60:63]
	v_mfma_f32_16x16x32_bf16 v[56:59], v[140:143], v[184:187], v[56:59]
	v_mfma_f32_16x16x32_bf16 v[52:55], v[132:135], v[192:195], v[52:55]
	v_mfma_f32_16x16x32_bf16 v[44:47], v[140:143], v[192:195], v[44:47]
	v_mfma_f32_16x16x32_bf16 v[36:39], v[132:135], v[200:203], v[36:39]
	v_mfma_f32_16x16x32_bf16 v[28:31], v[140:143], v[200:203], v[28:31]
	v_mfma_f32_16x16x32_bf16 v[20:23], v[132:135], v[208:211], v[20:23]
	v_mfma_f32_16x16x32_bf16 v[12:15], v[140:143], v[208:211], v[12:15]
	s_setprio 0
	s_setprio 1
	v_mfma_f32_16x16x32_bf16 v[48:51], v[162:165], v[178:181], v[48:51]
	v_mfma_f32_16x16x32_bf16 v[40:43], v[170:173], v[178:181], v[40:43]
	v_mfma_f32_16x16x32_bf16 v[32:35], v[162:165], v[188:191], v[32:35]
	v_mfma_f32_16x16x32_bf16 v[24:27], v[170:173], v[188:191], v[24:27]
	v_mfma_f32_16x16x32_bf16 v[16:19], v[162:165], v[196:199], v[16:19]
	v_mfma_f32_16x16x32_bf16 v[8:11], v[170:173], v[196:199], v[8:11]
	v_mfma_f32_16x16x32_bf16 v[4:7], v[162:165], v[204:207], v[4:7]
	v_mfma_f32_16x16x32_bf16 v[0:3], v[170:173], v[204:207], v[0:3]
	v_mfma_f32_16x16x32_bf16 v[48:51], v[166:169], v[184:187], v[48:51]
	v_mfma_f32_16x16x32_bf16 v[40:43], v[174:177], v[184:187], v[40:43]
	v_mfma_f32_16x16x32_bf16 v[32:35], v[166:169], v[192:195], v[32:35]
	v_mfma_f32_16x16x32_bf16 v[24:27], v[174:177], v[192:195], v[24:27]
	v_mfma_f32_16x16x32_bf16 v[16:19], v[166:169], v[200:203], v[16:19]
	v_mfma_f32_16x16x32_bf16 v[8:11], v[174:177], v[200:203], v[8:11]
	v_mfma_f32_16x16x32_bf16 v[4:7], v[166:169], v[208:211], v[4:7]
	v_mfma_f32_16x16x32_bf16 v[0:3], v[174:177], v[208:211], v[0:3]
	s_setprio 0
	s_barrier
	s_add_i32 s70, s70, 2
	s_add_u32 s28, s28, 0x100
	s_addc_u32 s29, s29, 0
	s_add_u32 s68, s68, 0x100
	s_addc_u32 s69, s69, 0
	s_cmpk_gt_u32 s70, 0xfd
	s_cbranch_scc0 .LBB0_937
	s_and_b64 vcc, exec, s[8:9]
	s_cbranch_vccz .LBB0_940
	s_barrier
